# as v8 plus nt on FFN-in SwiGLU activation stores and W_in projection output stores
# baseline (speedup 1.0000x reference)
.LBB0_214:
	s_lshl_b32 s15, s0, 8
	s_add_i32 s17, s15, 0xffffe100
	s_cmp_gt_i32 s0, 31
	s_cselect_b32 s0, s17, 0
	s_sub_i32 s0, s0, s15
	s_lshl_b32 s0, s0, 2
	s_add_i32 s0, s0, 0
	v_add_u32_e32 v160, s15, v149
	s_add_i32 s0, s0, 0x20000
	v_lshl_add_u32 v159, v160, 2, s0
	ds_read2st64_b32 v[144:145], v159 offset1:2
	v_lshl_or_b32 v162, s40, 7, v151
	v_ashrrev_i32_e32 v163, 31, v162
	s_mov_b64 s[40:41], -1
	s_andn2_b64 vcc, exec, s[18:19]
	s_waitcnt lgkmcnt(0)
	v_pk_mul_f32 v[126:127], v[126:127], v[144:145] op_sel_hi:[1,0]
	v_pk_mul_f32 v[122:123], v[122:123], v[144:145] op_sel_hi:[1,0]
	v_mul_f32_e32 v161, 0xbfb8aa3b, v126
	v_exp_f32_e32 v161, v161
	v_pk_mul_f32 v[124:125], v[124:125], v[144:145] op_sel_hi:[1,0]
	v_pk_mul_f32 v[118:119], v[118:119], v[144:145] op_sel_hi:[1,0]
	v_pk_mul_f32 v[114:115], v[114:115], v[144:145] op_sel_hi:[1,0]
	v_add_f32_e32 v161, 1.0, v161
	v_rcp_f32_e32 v164, v161
	v_mul_f32_e32 v161, 0xbfb8aa3b, v127
	v_exp_f32_e32 v161, v161
	v_pk_mul_f32 v[116:117], v[116:117], v[144:145] op_sel_hi:[1,0]
	v_add_f32_e32 v161, 1.0, v161
	v_rcp_f32_e32 v165, v161
	s_nop 0
	v_pk_mul_f32 v[126:127], v[126:127], v[164:165]
	s_nop 0
	v_pk_mul_f32 v[122:123], v[122:123], v[126:127]
	v_pk_mul_f32 v[126:127], v[128:129], v[144:145] op_sel_hi:[1,0]
	s_nop 0
	v_mul_f32_e32 v128, 0xbfb8aa3b, v126
	v_mul_f32_e32 v129, 0xbfb8aa3b, v127
	v_exp_f32_e32 v128, v128
	v_exp_f32_e32 v129, v129
	v_add_f32_e32 v128, 1.0, v128
	v_add_f32_e32 v129, 1.0, v129
	v_rcp_f32_e32 v128, v128
	v_rcp_f32_e32 v129, v129
	s_nop 0
	v_pk_mul_f32 v[126:127], v[126:127], v[128:129]
	s_nop 0
	v_pk_mul_f32 v[124:125], v[124:125], v[126:127]
	v_mul_f32_e32 v126, 0xbfb8aa3b, v118
	v_mul_f32_e32 v127, 0xbfb8aa3b, v119
	v_exp_f32_e32 v126, v126
	v_exp_f32_e32 v127, v127
	v_add_f32_e32 v126, 1.0, v126
	v_add_f32_e32 v127, 1.0, v127
	v_rcp_f32_e32 v126, v126
	v_rcp_f32_e32 v127, v127
	s_nop 0
	v_pk_mul_f32 v[118:119], v[118:119], v[126:127]
	s_nop 0
	v_pk_mul_f32 v[114:115], v[114:115], v[118:119]
	v_pk_mul_f32 v[118:119], v[120:121], v[144:145] op_sel_hi:[1,0]
	s_nop 0
	v_mul_f32_e32 v120, 0xbfb8aa3b, v118
	v_mul_f32_e32 v121, 0xbfb8aa3b, v119
	v_exp_f32_e32 v120, v120
	v_exp_f32_e32 v121, v121
	v_add_f32_e32 v120, 1.0, v120
	v_add_f32_e32 v121, 1.0, v121
	v_rcp_f32_e32 v120, v120
	v_rcp_f32_e32 v121, v121
	s_nop 0
	v_pk_mul_f32 v[118:119], v[118:119], v[120:121]
	s_nop 0
	v_pk_mul_f32 v[116:117], v[116:117], v[118:119]
	v_cvt_pk_bf16_f32 v120, v114, v115
	v_mov_b64_e32 v[114:115], s[6:7]
	v_cvt_pk_bf16_f32 v118, v122, v123
	v_cvt_pk_bf16_f32 v121, v116, v117
	v_mad_i64_i32 v[122:123], s[20:21], v160, s84, v[114:115]
	v_lshlrev_b64 v[116:117], 1, v[162:163]
	v_cvt_pk_bf16_f32 v119, v124, v125
	v_lshl_add_u64 v[122:123], v[122:123], 0, v[116:117]
	global_store_dwordx4 v[122:123], v[118:121], off nt
	s_nop 1
	v_or_b32_e32 v119, 16, v160
	v_lshl_add_u32 v118, v119, 2, s0
	ds_read_b32 v118, v118
	s_waitcnt lgkmcnt(0)
	v_pk_mul_f32 v[110:111], v[110:111], v[118:119] op_sel_hi:[1,0]
	s_nop 0
	v_mul_f32_e32 v120, 0xbfb8aa3b, v110
	v_mul_f32_e32 v121, 0xbfb8aa3b, v111
	v_exp_f32_e32 v120, v120
	v_exp_f32_e32 v121, v121
	v_pk_mul_f32 v[102:103], v[102:103], v[118:119] op_sel_hi:[1,0]
	v_pk_mul_f32 v[104:105], v[104:105], v[118:119] op_sel_hi:[1,0]
	v_add_f32_e32 v120, 1.0, v120
	v_add_f32_e32 v121, 1.0, v121
	v_rcp_f32_e32 v120, v120
	v_rcp_f32_e32 v121, v121
	v_pk_mul_f32 v[106:107], v[106:107], v[118:119] op_sel_hi:[1,0]
	v_pk_mul_f32 v[98:99], v[98:99], v[118:119] op_sel_hi:[1,0]
	v_pk_mul_f32 v[100:101], v[100:101], v[118:119] op_sel_hi:[1,0]
	v_pk_mul_f32 v[110:111], v[110:111], v[120:121]
	s_nop 0
	v_pk_mul_f32 v[102:103], v[102:103], v[110:111]
	v_pk_mul_f32 v[110:111], v[112:113], v[118:119] op_sel_hi:[1,0]
	s_nop 0
	v_mul_f32_e32 v112, 0xbfb8aa3b, v110
	v_mul_f32_e32 v113, 0xbfb8aa3b, v111
	v_exp_f32_e32 v112, v112
	v_exp_f32_e32 v113, v113
	v_add_f32_e32 v112, 1.0, v112
	v_add_f32_e32 v113, 1.0, v113
	v_rcp_f32_e32 v112, v112
	v_rcp_f32_e32 v113, v113
	s_nop 0
	v_pk_mul_f32 v[110:111], v[110:111], v[112:113]
	s_nop 0
	v_pk_mul_f32 v[104:105], v[104:105], v[110:111]
	v_mul_f32_e32 v110, 0xbfb8aa3b, v106
	v_mul_f32_e32 v111, 0xbfb8aa3b, v107
	v_exp_f32_e32 v110, v110
	v_exp_f32_e32 v111, v111
	v_add_f32_e32 v110, 1.0, v110
	v_add_f32_e32 v111, 1.0, v111
	v_rcp_f32_e32 v110, v110
	v_rcp_f32_e32 v111, v111
	s_nop 0
	v_pk_mul_f32 v[106:107], v[106:107], v[110:111]
	s_nop 0
	v_pk_mul_f32 v[106:107], v[98:99], v[106:107]
	v_pk_mul_f32 v[98:99], v[108:109], v[118:119] op_sel_hi:[1,0]
	s_nop 0
	v_mul_f32_e32 v108, 0xbfb8aa3b, v98
	v_mul_f32_e32 v109, 0xbfb8aa3b, v99
	v_exp_f32_e32 v108, v108
	v_exp_f32_e32 v109, v109
	v_add_f32_e32 v108, 1.0, v108
	v_add_f32_e32 v109, 1.0, v109
	v_rcp_f32_e32 v108, v108
	v_rcp_f32_e32 v109, v109
	s_nop 0
	v_pk_mul_f32 v[98:99], v[98:99], v[108:109]
	s_nop 0
	v_pk_mul_f32 v[108:109], v[100:101], v[98:99]
	v_cvt_pk_bf16_f32 v98, v102, v103
	v_mad_i64_i32 v[102:103], s[20:21], v119, s84, v[114:115]
	v_cvt_pk_bf16_f32 v99, v104, v105
	v_cvt_pk_bf16_f32 v100, v106, v107
	v_cvt_pk_bf16_f32 v101, v108, v109
	v_lshl_add_u64 v[102:103], v[102:103], 0, v[116:117]
	global_store_dwordx4 v[102:103], v[98:101], off nt
	s_nop 1
	v_or_b32_e32 v99, 32, v160
	v_lshl_add_u32 v98, v99, 2, s0
	ds_read_b32 v98, v98
	s_waitcnt lgkmcnt(0)
	v_pk_mul_f32 v[94:95], v[94:95], v[98:99] op_sel_hi:[1,0]
	s_nop 0
	v_mul_f32_e32 v100, 0xbfb8aa3b, v94
	v_mul_f32_e32 v101, 0xbfb8aa3b, v95
	v_exp_f32_e32 v100, v100
	v_exp_f32_e32 v101, v101
	v_pk_mul_f32 v[86:87], v[86:87], v[98:99] op_sel_hi:[1,0]
	v_pk_mul_f32 v[88:89], v[88:89], v[98:99] op_sel_hi:[1,0]
	v_add_f32_e32 v100, 1.0, v100
	v_add_f32_e32 v101, 1.0, v101
	v_rcp_f32_e32 v100, v100
	v_rcp_f32_e32 v101, v101
	v_pk_mul_f32 v[90:91], v[90:91], v[98:99] op_sel_hi:[1,0]
	v_pk_mul_f32 v[82:83], v[82:83], v[98:99] op_sel_hi:[1,0]
	v_pk_mul_f32 v[84:85], v[84:85], v[98:99] op_sel_hi:[1,0]
	v_pk_mul_f32 v[94:95], v[94:95], v[100:101]
	s_nop 0
	v_pk_mul_f32 v[86:87], v[86:87], v[94:95]
	v_pk_mul_f32 v[94:95], v[96:97], v[98:99] op_sel_hi:[1,0]
	s_nop 0
	v_mul_f32_e32 v96, 0xbfb8aa3b, v94
	v_mul_f32_e32 v97, 0xbfb8aa3b, v95
	v_exp_f32_e32 v96, v96
	v_exp_f32_e32 v97, v97
	v_add_f32_e32 v96, 1.0, v96
	v_add_f32_e32 v97, 1.0, v97
	v_rcp_f32_e32 v96, v96
	v_rcp_f32_e32 v97, v97
	s_nop 0
	v_pk_mul_f32 v[94:95], v[94:95], v[96:97]
	s_nop 0
	v_pk_mul_f32 v[88:89], v[88:89], v[94:95]
	v_mul_f32_e32 v94, 0xbfb8aa3b, v90
	v_mul_f32_e32 v95, 0xbfb8aa3b, v91
	v_exp_f32_e32 v94, v94
	v_exp_f32_e32 v95, v95
	v_add_f32_e32 v94, 1.0, v94
	v_add_f32_e32 v95, 1.0, v95
	v_rcp_f32_e32 v94, v94
	v_rcp_f32_e32 v95, v95
	s_nop 0
	v_pk_mul_f32 v[90:91], v[90:91], v[94:95]
	s_nop 0
	v_pk_mul_f32 v[90:91], v[82:83], v[90:91]
	v_pk_mul_f32 v[82:83], v[92:93], v[98:99] op_sel_hi:[1,0]
	s_nop 0
	v_mul_f32_e32 v92, 0xbfb8aa3b, v82
	v_mul_f32_e32 v93, 0xbfb8aa3b, v83
	v_exp_f32_e32 v92, v92
	v_exp_f32_e32 v93, v93
	v_add_f32_e32 v92, 1.0, v92
	v_add_f32_e32 v93, 1.0, v93
	v_rcp_f32_e32 v92, v92
	v_rcp_f32_e32 v93, v93
	s_nop 0
	v_pk_mul_f32 v[82:83], v[82:83], v[92:93]
	s_nop 0
	v_pk_mul_f32 v[92:93], v[84:85], v[82:83]
	v_cvt_pk_bf16_f32 v82, v86, v87
	v_mad_i64_i32 v[86:87], s[20:21], v99, s84, v[114:115]
	v_cvt_pk_bf16_f32 v83, v88, v89
	v_cvt_pk_bf16_f32 v84, v90, v91
	v_cvt_pk_bf16_f32 v85, v92, v93
	v_lshl_add_u64 v[86:87], v[86:87], 0, v[116:117]
	global_store_dwordx4 v[86:87], v[82:85], off nt
	s_nop 1
	v_or_b32_e32 v83, 48, v160
	v_lshl_add_u32 v82, v83, 2, s0
	ds_read_b32 v82, v82
	s_waitcnt lgkmcnt(0)
	v_pk_mul_f32 v[78:79], v[78:79], v[82:83] op_sel_hi:[1,0]
	s_nop 0
	v_mul_f32_e32 v84, 0xbfb8aa3b, v78
	v_mul_f32_e32 v85, 0xbfb8aa3b, v79
	v_exp_f32_e32 v84, v84
	v_exp_f32_e32 v85, v85
	v_pk_mul_f32 v[70:71], v[70:71], v[82:83] op_sel_hi:[1,0]
	v_pk_mul_f32 v[72:73], v[72:73], v[82:83] op_sel_hi:[1,0]
	v_add_f32_e32 v84, 1.0, v84
	v_add_f32_e32 v85, 1.0, v85
	v_rcp_f32_e32 v84, v84
	v_rcp_f32_e32 v85, v85
	v_pk_mul_f32 v[74:75], v[74:75], v[82:83] op_sel_hi:[1,0]
	v_pk_mul_f32 v[66:67], v[66:67], v[82:83] op_sel_hi:[1,0]
	v_pk_mul_f32 v[68:69], v[68:69], v[82:83] op_sel_hi:[1,0]
	v_pk_mul_f32 v[78:79], v[78:79], v[84:85]
	s_nop 0
	v_pk_mul_f32 v[70:71], v[70:71], v[78:79]
	v_pk_mul_f32 v[78:79], v[80:81], v[82:83] op_sel_hi:[1,0]
	s_nop 0
	v_mul_f32_e32 v80, 0xbfb8aa3b, v78
	v_mul_f32_e32 v81, 0xbfb8aa3b, v79
	v_exp_f32_e32 v80, v80
	v_exp_f32_e32 v81, v81
	v_add_f32_e32 v80, 1.0, v80
	v_add_f32_e32 v81, 1.0, v81
	v_rcp_f32_e32 v80, v80
	v_rcp_f32_e32 v81, v81
	s_nop 0
	v_pk_mul_f32 v[78:79], v[78:79], v[80:81]
	s_nop 0
	v_pk_mul_f32 v[72:73], v[72:73], v[78:79]
	v_mul_f32_e32 v78, 0xbfb8aa3b, v74
	v_mul_f32_e32 v79, 0xbfb8aa3b, v75
	v_exp_f32_e32 v78, v78
	v_exp_f32_e32 v79, v79
	v_add_f32_e32 v78, 1.0, v78
	v_add_f32_e32 v79, 1.0, v79
	v_rcp_f32_e32 v78, v78
	v_rcp_f32_e32 v79, v79
	s_nop 0
	v_pk_mul_f32 v[74:75], v[74:75], v[78:79]
	s_nop 0
	v_pk_mul_f32 v[74:75], v[66:67], v[74:75]
	v_pk_mul_f32 v[66:67], v[76:77], v[82:83] op_sel_hi:[1,0]
	s_nop 0
	v_mul_f32_e32 v76, 0xbfb8aa3b, v66
	v_mul_f32_e32 v77, 0xbfb8aa3b, v67
	v_exp_f32_e32 v76, v76
	v_exp_f32_e32 v77, v77
	v_add_f32_e32 v76, 1.0, v76
	v_add_f32_e32 v77, 1.0, v77
	v_rcp_f32_e32 v76, v76
	v_rcp_f32_e32 v77, v77
	s_nop 0
	v_pk_mul_f32 v[66:67], v[66:67], v[76:77]
	s_nop 0
	v_pk_mul_f32 v[76:77], v[68:69], v[66:67]
	v_cvt_pk_bf16_f32 v66, v70, v71
	v_mad_i64_i32 v[70:71], s[20:21], v83, s84, v[114:115]
	v_cvt_pk_bf16_f32 v67, v72, v73
	v_cvt_pk_bf16_f32 v68, v74, v75
	v_cvt_pk_bf16_f32 v69, v76, v77
	v_lshl_add_u64 v[70:71], v[70:71], 0, v[116:117]
	global_store_dwordx4 v[70:71], v[66:69], off nt
	s_nop 1
	v_add_u32_e32 v67, 0x80, v160
	v_mov_b32_e32 v66, v145
	v_pk_mul_f32 v[62:63], v[62:63], v[66:67] op_sel_hi:[1,0]
	v_pk_mul_f32 v[54:55], v[54:55], v[66:67] op_sel_hi:[1,0]
	v_mul_f32_e32 v68, 0xbfb8aa3b, v62
	v_mul_f32_e32 v69, 0xbfb8aa3b, v63
	v_exp_f32_e32 v68, v68
	v_exp_f32_e32 v69, v69
	v_pk_mul_f32 v[56:57], v[56:57], v[66:67] op_sel_hi:[1,0]
	v_pk_mul_f32 v[58:59], v[58:59], v[66:67] op_sel_hi:[1,0]
	v_add_f32_e32 v68, 1.0, v68
	v_add_f32_e32 v69, 1.0, v69
	v_rcp_f32_e32 v68, v68
	v_rcp_f32_e32 v69, v69
	v_pk_mul_f32 v[46:47], v[46:47], v[66:67] op_sel_hi:[1,0]
	v_pk_mul_f32 v[48:49], v[48:49], v[66:67] op_sel_hi:[1,0]
	v_pk_mul_f32 v[62:63], v[62:63], v[68:69]
	s_nop 0
	v_pk_mul_f32 v[54:55], v[54:55], v[62:63]
	v_pk_mul_f32 v[62:63], v[64:65], v[66:67] op_sel_hi:[1,0]
	s_nop 0
	v_mul_f32_e32 v64, 0xbfb8aa3b, v62
	v_mul_f32_e32 v65, 0xbfb8aa3b, v63
	v_exp_f32_e32 v64, v64
	v_exp_f32_e32 v65, v65
	v_add_f32_e32 v64, 1.0, v64
	v_add_f32_e32 v65, 1.0, v65
	v_rcp_f32_e32 v64, v64
	v_rcp_f32_e32 v65, v65
	s_nop 0
	v_pk_mul_f32 v[62:63], v[62:63], v[64:65]
	s_nop 0
	v_pk_mul_f32 v[56:57], v[56:57], v[62:63]
	v_mul_f32_e32 v62, 0xbfb8aa3b, v58
	v_mul_f32_e32 v63, 0xbfb8aa3b, v59
	v_exp_f32_e32 v62, v62
	v_exp_f32_e32 v63, v63
	v_add_f32_e32 v62, 1.0, v62
	v_add_f32_e32 v63, 1.0, v63
	v_rcp_f32_e32 v62, v62
	v_rcp_f32_e32 v63, v63
	s_nop 0
	v_pk_mul_f32 v[58:59], v[58:59], v[62:63]
	s_nop 0
	v_pk_mul_f32 v[58:59], v[46:47], v[58:59]
	v_pk_mul_f32 v[46:47], v[60:61], v[66:67] op_sel_hi:[1,0]
	s_nop 0
	v_mul_f32_e32 v60, 0xbfb8aa3b, v46
	v_mul_f32_e32 v61, 0xbfb8aa3b, v47
	v_exp_f32_e32 v60, v60
	v_exp_f32_e32 v61, v61
	v_add_f32_e32 v60, 1.0, v60
	v_add_f32_e32 v61, 1.0, v61
	v_rcp_f32_e32 v60, v60
	v_rcp_f32_e32 v61, v61
	s_nop 0
	v_pk_mul_f32 v[46:47], v[46:47], v[60:61]
	s_nop 0
	v_pk_mul_f32 v[60:61], v[48:49], v[46:47]
	v_cvt_pk_bf16_f32 v46, v54, v55
	v_mad_i64_i32 v[54:55], s[20:21], v67, s84, v[114:115]
	v_cvt_pk_bf16_f32 v47, v56, v57
	v_cvt_pk_bf16_f32 v48, v58, v59
	v_cvt_pk_bf16_f32 v49, v60, v61
	v_lshl_add_u64 v[54:55], v[54:55], 0, v[116:117]
	global_store_dwordx4 v[54:55], v[46:49], off nt
	ds_read2_b32 v[46:47], v159 offset0:144 offset1:160
	v_add_u32_e32 v54, 0x90, v160
	s_waitcnt lgkmcnt(0)
	v_pk_mul_f32 v[48:49], v[50:51], v[46:47] op_sel_hi:[1,0]
	s_nop 0
	v_mul_f32_e32 v50, 0xbfb8aa3b, v48
	v_mul_f32_e32 v51, 0xbfb8aa3b, v49
	v_exp_f32_e32 v50, v50
	v_exp_f32_e32 v51, v51
	v_pk_mul_f32 v[38:39], v[38:39], v[46:47] op_sel_hi:[1,0]
	v_pk_mul_f32 v[40:41], v[40:41], v[46:47] op_sel_hi:[1,0]
	v_add_f32_e32 v50, 1.0, v50
	v_add_f32_e32 v51, 1.0, v51
	v_rcp_f32_e32 v50, v50
	v_rcp_f32_e32 v51, v51
	v_pk_mul_f32 v[42:43], v[42:43], v[46:47] op_sel_hi:[1,0]
	v_pk_mul_f32 v[30:31], v[30:31], v[46:47] op_sel_hi:[1,0]
	v_pk_mul_f32 v[32:33], v[32:33], v[46:47] op_sel_hi:[1,0]
	v_pk_mul_f32 v[48:49], v[48:49], v[50:51]
	s_nop 0
	v_pk_mul_f32 v[38:39], v[38:39], v[48:49]
	v_pk_mul_f32 v[48:49], v[52:53], v[46:47] op_sel_hi:[1,0]
	s_nop 0
	v_mul_f32_e32 v50, 0xbfb8aa3b, v48
	v_mul_f32_e32 v51, 0xbfb8aa3b, v49
	v_exp_f32_e32 v50, v50
	v_exp_f32_e32 v51, v51
	v_add_f32_e32 v50, 1.0, v50
	v_add_f32_e32 v51, 1.0, v51
	v_rcp_f32_e32 v50, v50
	v_rcp_f32_e32 v51, v51
	s_nop 0
	v_pk_mul_f32 v[48:49], v[48:49], v[50:51]
	s_nop 0
	v_pk_mul_f32 v[40:41], v[40:41], v[48:49]
	v_mul_f32_e32 v48, 0xbfb8aa3b, v42
	v_mul_f32_e32 v49, 0xbfb8aa3b, v43
	v_exp_f32_e32 v48, v48
	v_exp_f32_e32 v49, v49
	v_add_f32_e32 v48, 1.0, v48
	v_add_f32_e32 v49, 1.0, v49
	v_rcp_f32_e32 v48, v48
	v_rcp_f32_e32 v49, v49
	s_nop 0
	v_pk_mul_f32 v[42:43], v[42:43], v[48:49]
	s_nop 0
	v_pk_mul_f32 v[42:43], v[30:31], v[42:43]
	v_pk_mul_f32 v[30:31], v[44:45], v[46:47] op_sel_hi:[1,0]
	s_nop 0
	v_mul_f32_e32 v44, 0xbfb8aa3b, v30
	v_mul_f32_e32 v45, 0xbfb8aa3b, v31
	v_exp_f32_e32 v44, v44
	v_exp_f32_e32 v45, v45
	v_add_f32_e32 v44, 1.0, v44
	v_add_f32_e32 v45, 1.0, v45
	v_rcp_f32_e32 v44, v44
	v_rcp_f32_e32 v45, v45
	s_nop 0
	v_pk_mul_f32 v[30:31], v[30:31], v[44:45]
	s_nop 0
	v_pk_mul_f32 v[44:45], v[32:33], v[30:31]
	v_cvt_pk_bf16_f32 v30, v38, v39
	v_mad_i64_i32 v[38:39], s[20:21], v54, s84, v[114:115]
	v_cvt_pk_bf16_f32 v31, v40, v41
	v_cvt_pk_bf16_f32 v32, v42, v43
	v_cvt_pk_bf16_f32 v33, v44, v45
	v_lshl_add_u64 v[38:39], v[38:39], 0, v[116:117]
	global_store_dwordx4 v[38:39], v[30:33], off nt
	s_nop 1
	v_add_u32_e32 v31, 0xa0, v160
	v_mov_b32_e32 v30, v47
	v_pk_mul_f32 v[32:33], v[34:35], v[30:31] op_sel_hi:[1,0]
	v_pk_mul_f32 v[22:23], v[22:23], v[30:31] op_sel_hi:[1,0]
	v_mul_f32_e32 v34, 0xbfb8aa3b, v32
	v_mul_f32_e32 v35, 0xbfb8aa3b, v33
	v_exp_f32_e32 v34, v34
	v_exp_f32_e32 v35, v35
	v_pk_mul_f32 v[24:25], v[24:25], v[30:31] op_sel_hi:[1,0]
	v_pk_mul_f32 v[26:27], v[26:27], v[30:31] op_sel_hi:[1,0]
	v_add_f32_e32 v34, 1.0, v34
	v_add_f32_e32 v35, 1.0, v35
	v_rcp_f32_e32 v34, v34
	v_rcp_f32_e32 v35, v35
	v_pk_mul_f32 v[18:19], v[18:19], v[30:31] op_sel_hi:[1,0]
	v_pk_mul_f32 v[20:21], v[20:21], v[30:31] op_sel_hi:[1,0]
	v_pk_mul_f32 v[32:33], v[32:33], v[34:35]
	s_nop 0
	v_pk_mul_f32 v[22:23], v[22:23], v[32:33]
	v_pk_mul_f32 v[32:33], v[36:37], v[30:31] op_sel_hi:[1,0]
	s_nop 0
	v_mul_f32_e32 v34, 0xbfb8aa3b, v32
	v_mul_f32_e32 v35, 0xbfb8aa3b, v33
	v_exp_f32_e32 v34, v34
	v_exp_f32_e32 v35, v35
	v_add_f32_e32 v34, 1.0, v34
	v_add_f32_e32 v35, 1.0, v35
	v_rcp_f32_e32 v34, v34
	v_rcp_f32_e32 v35, v35
	s_nop 0
	v_pk_mul_f32 v[32:33], v[32:33], v[34:35]
	s_nop 0
	v_pk_mul_f32 v[24:25], v[24:25], v[32:33]
	v_mul_f32_e32 v32, 0xbfb8aa3b, v26
	v_mul_f32_e32 v33, 0xbfb8aa3b, v27
	v_exp_f32_e32 v32, v32
	v_exp_f32_e32 v33, v33
	v_add_f32_e32 v32, 1.0, v32
	v_add_f32_e32 v33, 1.0, v33
	v_rcp_f32_e32 v32, v32
	v_rcp_f32_e32 v33, v33
	s_nop 0
	v_pk_mul_f32 v[26:27], v[26:27], v[32:33]
	s_nop 0
	v_pk_mul_f32 v[26:27], v[18:19], v[26:27]
	v_pk_mul_f32 v[18:19], v[28:29], v[30:31] op_sel_hi:[1,0]
	s_nop 0
	v_mul_f32_e32 v28, 0xbfb8aa3b, v18
	v_mul_f32_e32 v29, 0xbfb8aa3b, v19
	v_exp_f32_e32 v28, v28
	v_exp_f32_e32 v29, v29
	v_add_f32_e32 v28, 1.0, v28
	v_add_f32_e32 v29, 1.0, v29
	v_rcp_f32_e32 v28, v28
	v_rcp_f32_e32 v29, v29
	s_nop 0
	v_pk_mul_f32 v[18:19], v[18:19], v[28:29]
	s_nop 0
	v_pk_mul_f32 v[28:29], v[20:21], v[18:19]
	v_cvt_pk_bf16_f32 v18, v22, v23
	v_mad_i64_i32 v[22:23], s[20:21], v31, s84, v[114:115]
	v_cvt_pk_bf16_f32 v19, v24, v25
	v_cvt_pk_bf16_f32 v20, v26, v27
	v_cvt_pk_bf16_f32 v21, v28, v29
	v_lshl_add_u64 v[22:23], v[22:23], 0, v[116:117]
	global_store_dwordx4 v[22:23], v[18:21], off nt
	ds_read_b32 v18, v159 offset:704
	s_nop 0
	v_add_u32_e32 v19, 0xb0, v160
	s_waitcnt lgkmcnt(0)
	v_pk_mul_f32 v[14:15], v[14:15], v[18:19] op_sel_hi:[1,0]
	s_nop 0
	v_mul_f32_e32 v20, 0xbfb8aa3b, v14
	v_mul_f32_e32 v21, 0xbfb8aa3b, v15
	v_exp_f32_e32 v20, v20
	v_exp_f32_e32 v21, v21
	v_pk_mul_f32 v[10:11], v[10:11], v[18:19] op_sel_hi:[1,0]
	v_pk_mul_f32 v[12:13], v[12:13], v[18:19] op_sel_hi:[1,0]
	v_add_f32_e32 v20, 1.0, v20
	v_add_f32_e32 v21, 1.0, v21
	v_rcp_f32_e32 v20, v20
	v_rcp_f32_e32 v21, v21
	v_pk_mul_f32 v[6:7], v[6:7], v[18:19] op_sel_hi:[1,0]
	v_pk_mul_f32 v[2:3], v[2:3], v[18:19] op_sel_hi:[1,0]
	v_pk_mul_f32 v[4:5], v[4:5], v[18:19] op_sel_hi:[1,0]
	v_pk_mul_f32 v[14:15], v[14:15], v[20:21]
	s_nop 0
	v_pk_mul_f32 v[10:11], v[10:11], v[14:15]
	v_pk_mul_f32 v[14:15], v[16:17], v[18:19] op_sel_hi:[1,0]
	s_nop 0
	v_mul_f32_e32 v16, 0xbfb8aa3b, v14
	v_mul_f32_e32 v17, 0xbfb8aa3b, v15
	v_exp_f32_e32 v16, v16
	v_exp_f32_e32 v17, v17
	v_add_f32_e32 v16, 1.0, v16
	v_add_f32_e32 v17, 1.0, v17
	v_rcp_f32_e32 v16, v16
	v_rcp_f32_e32 v17, v17
	s_nop 0
	v_pk_mul_f32 v[14:15], v[14:15], v[16:17]
	s_nop 0
	v_pk_mul_f32 v[12:13], v[12:13], v[14:15]
	v_mul_f32_e32 v14, 0xbfb8aa3b, v6
	v_mul_f32_e32 v15, 0xbfb8aa3b, v7
	v_exp_f32_e32 v14, v14
	v_exp_f32_e32 v15, v15
	v_add_f32_e32 v14, 1.0, v14
	v_add_f32_e32 v15, 1.0, v15
	v_rcp_f32_e32 v14, v14
	v_rcp_f32_e32 v15, v15
	s_nop 0
	v_pk_mul_f32 v[6:7], v[6:7], v[14:15]
	s_nop 0
	v_pk_mul_f32 v[6:7], v[2:3], v[6:7]
	v_pk_mul_f32 v[2:3], v[8:9], v[18:19] op_sel_hi:[1,0]
	s_nop 0
	v_mul_f32_e32 v8, 0xbfb8aa3b, v2
	v_mul_f32_e32 v9, 0xbfb8aa3b, v3
	v_exp_f32_e32 v8, v8
	v_exp_f32_e32 v9, v9
	v_add_f32_e32 v8, 1.0, v8
	v_add_f32_e32 v9, 1.0, v9
	v_rcp_f32_e32 v8, v8
	v_rcp_f32_e32 v9, v9
	s_nop 0
	v_pk_mul_f32 v[2:3], v[2:3], v[8:9]
	s_nop 0
	v_pk_mul_f32 v[8:9], v[4:5], v[2:3]
	v_cvt_pk_bf16_f32 v4, v6, v7
	v_mad_i64_i32 v[6:7], s[20:21], v19, s84, v[114:115]
	v_cvt_pk_bf16_f32 v2, v10, v11
	v_cvt_pk_bf16_f32 v3, v12, v13
	v_cvt_pk_bf16_f32 v5, v8, v9
	v_lshl_add_u64 v[6:7], v[6:7], 0, v[116:117]
	global_store_dwordx4 v[6:7], v[2:5], off nt
	s_cbranch_vccnz .LBB0_204
	s_andn2_b64 vcc, exec, s[2:3]
	s_cbranch_vccnz .LBB0_203
	s_barrier
	s_branch .LBB0_203

.LBB0_652:
	s_lshl_b32 s1, s0, 8
	s_add_i32 s4, s1, s21
	s_add_i32 s5, s1, 0xffffe100
	s_cmp_gt_i32 s0, 31
	s_cselect_b32 s0, s5, 0
	s_sub_i32 s5, s0, s1
	v_or_b32_e32 v146, s4, v1
	s_cmp_gt_i32 s6, 25
	s_mov_b64 s[0:1], -1
	s_cbranch_scc0 .LBB0_663
	s_cmp_gt_u32 s6, 37
	s_cbranch_scc0 .LBB0_659
	s_lshl_b32 s7, s6, 8
	s_cmp_gt_u32 s6, 41
	s_cbranch_scc0 .LBB0_656
	s_lshl_b32 s0, s5, 2
	s_add_i32 s0, s0, 0
	s_add_i32 s0, s0, 0x20000
	v_lshl_add_u32 v147, v146, 2, s0
	ds_read2st64_b32 v[150:151], v147 offset1:2
	v_mov_b64_e32 v[148:149], s[74:75]
	v_add_u32_e32 v140, s7, v158
	v_mad_i64_i32 v[152:153], s[8:9], v146, s88, v[148:149]
	s_waitcnt lgkmcnt(0)
	v_mul_f32_e32 v154, v126, v150
	v_mul_f32_e32 v154, 0xbfb8aa3b, v154
	v_mul_f32_e32 v155, v127, v150
	v_exp_f32_e32 v154, v154
	v_mul_f32_e32 v155, 0xbfb8aa3b, v155
	v_mul_f32_e32 v164, v128, v150
	v_exp_f32_e32 v155, v155
	v_mul_f32_e32 v164, 0xbfb8aa3b, v164
	v_mul_f32_e32 v165, v129, v150
	v_exp_f32_e32 v164, v164
	v_mul_f32_e32 v165, 0xbfb8aa3b, v165
	v_exp_f32_e32 v165, v165
	v_add_f32_e32 v154, 1.0, v154
	v_rcp_f32_e32 v154, v154
	v_add_f32_e32 v155, 1.0, v155
	v_rcp_f32_e32 v155, v155
	v_add_f32_e32 v164, 1.0, v164
	v_rcp_f32_e32 v164, v164
	v_add_f32_e32 v165, 1.0, v165
	v_rcp_f32_e32 v165, v165
	v_mul_f32_e32 v154, 0x437f0000, v154
	v_max_f32_e32 v154, 1.0, v154
	v_mul_f32_e32 v155, 0x437f0000, v155
	v_max_f32_e32 v155, 1.0, v155
	v_mul_f32_e32 v164, 0x437f0000, v164
	v_cvt_pk_u8_f32 v154, v154, 0, 0
	v_max_f32_e32 v164, 1.0, v164
	v_mul_f32_e32 v165, 0x437f0000, v165
	v_cvt_pk_u8_f32 v154, v155, 1, v154
	v_mul_f32_e32 v155, v122, v150
	v_max_f32_e32 v165, 1.0, v165
	v_cvt_pk_u8_f32 v154, v164, 2, v154
	v_mul_f32_e32 v155, 0xbfb8aa3b, v155
	v_mul_f32_e32 v164, v123, v150
	v_cvt_pk_u8_f32 v154, v165, 3, v154
	v_exp_f32_e32 v155, v155
	v_mul_f32_e32 v164, 0xbfb8aa3b, v164
	v_mul_f32_e32 v165, v124, v150
	v_exp_f32_e32 v164, v164
	v_mul_f32_e32 v165, 0xbfb8aa3b, v165
	v_mul_f32_e32 v166, v125, v150
	v_exp_f32_e32 v165, v165
	v_mul_f32_e32 v166, 0xbfb8aa3b, v166
	v_exp_f32_e32 v166, v166
	v_add_f32_e32 v155, 1.0, v155
	v_rcp_f32_e32 v155, v155
	v_add_f32_e32 v164, 1.0, v164
	v_rcp_f32_e32 v164, v164
	v_add_f32_e32 v165, 1.0, v165
	v_rcp_f32_e32 v165, v165
	v_add_f32_e32 v166, 1.0, v166
	v_rcp_f32_e32 v166, v166
	v_mul_f32_e32 v155, 0x437f0000, v155
	v_max_f32_e32 v155, 1.0, v155
	v_mul_f32_e32 v164, 0x437f0000, v164
	v_max_f32_e32 v164, 1.0, v164
	v_mul_f32_e32 v165, 0x437f0000, v165
	v_cvt_pk_u8_f32 v155, v155, 0, 0
	v_max_f32_e32 v165, 1.0, v165
	v_mul_f32_e32 v166, 0x437f0000, v166
	v_cvt_pk_u8_f32 v155, v164, 1, v155
	v_max_f32_e32 v166, 1.0, v166
	v_cvt_pk_u8_f32 v155, v165, 2, v155
	v_lshl_add_u64 v[152:153], v[152:153], 0, v[140:141]
	v_cvt_pk_u8_f32 v155, v166, 3, v155
	global_store_dwordx2 v[152:153], v[154:155], off nt
	v_mul_f32_e32 v154, v118, v150
	v_mul_f32_e32 v154, 0xbfb8aa3b, v154
	v_mul_f32_e32 v155, v119, v150
	v_exp_f32_e32 v154, v154
	v_mul_f32_e32 v155, 0xbfb8aa3b, v155
	v_mul_f32_e32 v164, v120, v150
	v_exp_f32_e32 v155, v155
	v_mul_f32_e32 v164, 0xbfb8aa3b, v164
	v_mul_f32_e32 v165, v121, v150
	v_exp_f32_e32 v164, v164
	v_mul_f32_e32 v165, 0xbfb8aa3b, v165
	v_exp_f32_e32 v165, v165
	v_add_f32_e32 v154, 1.0, v154
	v_rcp_f32_e32 v154, v154
	v_add_f32_e32 v155, 1.0, v155
	v_rcp_f32_e32 v155, v155
	v_add_f32_e32 v164, 1.0, v164
	v_rcp_f32_e32 v164, v164
	v_add_f32_e32 v165, 1.0, v165
	v_rcp_f32_e32 v165, v165
	v_mul_f32_e32 v154, 0x437f0000, v154
	v_max_f32_e32 v154, 1.0, v154
	v_mul_f32_e32 v155, 0x437f0000, v155
	v_max_f32_e32 v155, 1.0, v155
	v_mul_f32_e32 v164, 0x437f0000, v164
	v_cvt_pk_u8_f32 v154, v154, 0, 0
	v_max_f32_e32 v164, 1.0, v164
	v_mul_f32_e32 v165, 0x437f0000, v165
	v_cvt_pk_u8_f32 v154, v155, 1, v154
	v_mul_f32_e32 v155, v114, v150
	v_max_f32_e32 v165, 1.0, v165
	v_cvt_pk_u8_f32 v154, v164, 2, v154
	v_mul_f32_e32 v155, 0xbfb8aa3b, v155
	v_mul_f32_e32 v164, v115, v150
	v_cvt_pk_u8_f32 v154, v165, 3, v154
	v_exp_f32_e32 v155, v155
	v_mul_f32_e32 v164, 0xbfb8aa3b, v164
	v_mul_f32_e32 v165, v116, v150
	v_exp_f32_e32 v164, v164
	v_mul_f32_e32 v165, 0xbfb8aa3b, v165
	v_mul_f32_e32 v150, v117, v150
	v_exp_f32_e32 v165, v165
	v_mul_f32_e32 v150, 0xbfb8aa3b, v150
	v_exp_f32_e32 v150, v150
	v_add_f32_e32 v155, 1.0, v155
	v_rcp_f32_e32 v155, v155
	v_add_f32_e32 v164, 1.0, v164
	v_rcp_f32_e32 v164, v164
	v_add_f32_e32 v165, 1.0, v165
	v_rcp_f32_e32 v165, v165
	v_add_f32_e32 v150, 1.0, v150
	v_rcp_f32_e32 v150, v150
	v_mul_f32_e32 v155, 0x437f0000, v155
	v_max_f32_e32 v155, 1.0, v155
	v_mul_f32_e32 v164, 0x437f0000, v164
	v_max_f32_e32 v164, 1.0, v164
	v_mul_f32_e32 v165, 0x437f0000, v165
	v_cvt_pk_u8_f32 v155, v155, 0, 0
	v_max_f32_e32 v165, 1.0, v165
	v_mul_f32_e32 v150, 0x437f0000, v150
	v_cvt_pk_u8_f32 v155, v164, 1, v155
	v_max_f32_e32 v150, 1.0, v150
	v_cvt_pk_u8_f32 v155, v165, 2, v155
	v_cvt_pk_u8_f32 v155, v150, 3, v155
	v_or_b32_e32 v150, 16, v146
	global_store_dwordx2 v[152:153], v[154:155], off offset:128 nt
	v_lshl_add_u32 v152, v150, 2, s0
	ds_read_b32 v164, v152
	v_mad_i64_i32 v[152:153], s[8:9], v150, s88, v[148:149]
	v_lshl_add_u64 v[152:153], v[152:153], 0, v[140:141]
	s_waitcnt lgkmcnt(0)
	v_mul_f32_e32 v150, v110, v164
	v_mul_f32_e32 v150, 0xbfb8aa3b, v150
	v_mul_f32_e32 v154, v111, v164
	v_exp_f32_e32 v150, v150
	v_mul_f32_e32 v154, 0xbfb8aa3b, v154
	v_mul_f32_e32 v155, v112, v164
	v_exp_f32_e32 v154, v154
	v_mul_f32_e32 v155, 0xbfb8aa3b, v155
	v_mul_f32_e32 v165, v113, v164
	v_exp_f32_e32 v155, v155
	v_mul_f32_e32 v165, 0xbfb8aa3b, v165
	v_exp_f32_e32 v165, v165
	v_add_f32_e32 v150, 1.0, v150
	v_rcp_f32_e32 v150, v150
	v_add_f32_e32 v154, 1.0, v154
	v_rcp_f32_e32 v154, v154
	v_add_f32_e32 v155, 1.0, v155
	v_rcp_f32_e32 v155, v155
	v_add_f32_e32 v165, 1.0, v165
	v_rcp_f32_e32 v165, v165
	v_mul_f32_e32 v150, 0x437f0000, v150
	v_max_f32_e32 v150, 1.0, v150
	v_mul_f32_e32 v154, 0x437f0000, v154
	v_max_f32_e32 v154, 1.0, v154
	v_mul_f32_e32 v155, 0x437f0000, v155
	v_cvt_pk_u8_f32 v150, v150, 0, 0
	v_max_f32_e32 v155, 1.0, v155
	v_mul_f32_e32 v165, 0x437f0000, v165
	v_cvt_pk_u8_f32 v150, v154, 1, v150
	v_max_f32_e32 v165, 1.0, v165
	v_cvt_pk_u8_f32 v150, v155, 2, v150
	v_cvt_pk_u8_f32 v154, v165, 3, v150
	v_mul_f32_e32 v150, v106, v164
	v_mul_f32_e32 v150, 0xbfb8aa3b, v150
	v_mul_f32_e32 v155, v107, v164
	v_exp_f32_e32 v150, v150
	v_mul_f32_e32 v155, 0xbfb8aa3b, v155
	v_mul_f32_e32 v165, v108, v164
	v_exp_f32_e32 v155, v155
	v_mul_f32_e32 v165, 0xbfb8aa3b, v165
	v_mul_f32_e32 v166, v109, v164
	v_exp_f32_e32 v165, v165
	v_mul_f32_e32 v166, 0xbfb8aa3b, v166
	v_exp_f32_e32 v166, v166
	v_add_f32_e32 v150, 1.0, v150
	v_rcp_f32_e32 v150, v150
	v_add_f32_e32 v155, 1.0, v155
	v_rcp_f32_e32 v155, v155
	v_add_f32_e32 v165, 1.0, v165
	v_rcp_f32_e32 v165, v165
	v_add_f32_e32 v166, 1.0, v166
	v_rcp_f32_e32 v166, v166
	v_mul_f32_e32 v150, 0x437f0000, v150
	v_max_f32_e32 v150, 1.0, v150
	v_mul_f32_e32 v155, 0x437f0000, v155
	v_max_f32_e32 v155, 1.0, v155
	v_mul_f32_e32 v165, 0x437f0000, v165
	v_cvt_pk_u8_f32 v150, v150, 0, 0
	v_max_f32_e32 v165, 1.0, v165
	v_mul_f32_e32 v166, 0x437f0000, v166
	v_cvt_pk_u8_f32 v150, v155, 1, v150
	v_max_f32_e32 v166, 1.0, v166
	v_cvt_pk_u8_f32 v150, v165, 2, v150
	v_cvt_pk_u8_f32 v155, v166, 3, v150
	v_mul_f32_e32 v150, v102, v164
	global_store_dwordx2 v[152:153], v[154:155], off nt
	v_mul_f32_e32 v150, 0xbfb8aa3b, v150
	v_mul_f32_e32 v154, v103, v164
	v_exp_f32_e32 v150, v150
	v_mul_f32_e32 v154, 0xbfb8aa3b, v154
	v_mul_f32_e32 v155, v104, v164
	v_exp_f32_e32 v154, v154
	v_mul_f32_e32 v155, 0xbfb8aa3b, v155
	v_mul_f32_e32 v165, v105, v164
	v_exp_f32_e32 v155, v155
	v_mul_f32_e32 v165, 0xbfb8aa3b, v165
	v_exp_f32_e32 v165, v165
	v_add_f32_e32 v150, 1.0, v150
	v_rcp_f32_e32 v150, v150
	v_add_f32_e32 v154, 1.0, v154
	v_rcp_f32_e32 v154, v154
	v_add_f32_e32 v155, 1.0, v155
	v_rcp_f32_e32 v155, v155
	v_add_f32_e32 v165, 1.0, v165
	v_rcp_f32_e32 v165, v165
	v_mul_f32_e32 v150, 0x437f0000, v150
	v_max_f32_e32 v150, 1.0, v150
	v_mul_f32_e32 v154, 0x437f0000, v154
	v_max_f32_e32 v154, 1.0, v154
	v_mul_f32_e32 v155, 0x437f0000, v155
	v_cvt_pk_u8_f32 v150, v150, 0, 0
	v_max_f32_e32 v155, 1.0, v155
	v_mul_f32_e32 v165, 0x437f0000, v165
	v_cvt_pk_u8_f32 v150, v154, 1, v150
	v_max_f32_e32 v165, 1.0, v165
	v_cvt_pk_u8_f32 v150, v155, 2, v150
	v_cvt_pk_u8_f32 v154, v165, 3, v150
	v_mul_f32_e32 v150, v98, v164
	v_mul_f32_e32 v150, 0xbfb8aa3b, v150
	v_mul_f32_e32 v155, v99, v164
	v_exp_f32_e32 v150, v150
	v_mul_f32_e32 v155, 0xbfb8aa3b, v155
	v_mul_f32_e32 v165, v100, v164
	v_exp_f32_e32 v155, v155
	v_mul_f32_e32 v165, 0xbfb8aa3b, v165
	v_mul_f32_e32 v164, v101, v164
	v_exp_f32_e32 v165, v165
	v_mul_f32_e32 v164, 0xbfb8aa3b, v164
	v_exp_f32_e32 v164, v164
	v_add_f32_e32 v150, 1.0, v150
	v_rcp_f32_e32 v150, v150
	v_add_f32_e32 v155, 1.0, v155
	v_rcp_f32_e32 v155, v155
	v_add_f32_e32 v165, 1.0, v165
	v_rcp_f32_e32 v165, v165
	v_add_f32_e32 v164, 1.0, v164
	v_rcp_f32_e32 v164, v164
	v_mul_f32_e32 v150, 0x437f0000, v150
	v_max_f32_e32 v150, 1.0, v150
	v_mul_f32_e32 v155, 0x437f0000, v155
	v_max_f32_e32 v155, 1.0, v155
	v_mul_f32_e32 v165, 0x437f0000, v165
	v_cvt_pk_u8_f32 v150, v150, 0, 0
	v_max_f32_e32 v165, 1.0, v165
	v_mul_f32_e32 v164, 0x437f0000, v164
	v_cvt_pk_u8_f32 v150, v155, 1, v150
	v_max_f32_e32 v164, 1.0, v164
	v_cvt_pk_u8_f32 v150, v165, 2, v150
	v_cvt_pk_u8_f32 v155, v164, 3, v150
	v_or_b32_e32 v150, 32, v146
	global_store_dwordx2 v[152:153], v[154:155], off offset:128 nt
	v_lshl_add_u32 v152, v150, 2, s0
	ds_read_b32 v164, v152
	v_mad_i64_i32 v[152:153], s[8:9], v150, s88, v[148:149]
	v_lshl_add_u64 v[152:153], v[152:153], 0, v[140:141]
	s_waitcnt lgkmcnt(0)
	v_mul_f32_e32 v150, v94, v164
	v_mul_f32_e32 v150, 0xbfb8aa3b, v150
	v_mul_f32_e32 v154, v95, v164
	v_exp_f32_e32 v150, v150
	v_mul_f32_e32 v154, 0xbfb8aa3b, v154
	v_mul_f32_e32 v155, v96, v164
	v_exp_f32_e32 v154, v154
	v_mul_f32_e32 v155, 0xbfb8aa3b, v155
	v_mul_f32_e32 v165, v97, v164
	v_exp_f32_e32 v155, v155
	v_mul_f32_e32 v165, 0xbfb8aa3b, v165
	v_exp_f32_e32 v165, v165
	v_add_f32_e32 v150, 1.0, v150
	v_rcp_f32_e32 v150, v150
	v_add_f32_e32 v154, 1.0, v154
	v_rcp_f32_e32 v154, v154
	v_add_f32_e32 v155, 1.0, v155
	v_rcp_f32_e32 v155, v155
	v_add_f32_e32 v165, 1.0, v165
	v_rcp_f32_e32 v165, v165
	v_mul_f32_e32 v150, 0x437f0000, v150
	v_max_f32_e32 v150, 1.0, v150
	v_mul_f32_e32 v154, 0x437f0000, v154
	v_max_f32_e32 v154, 1.0, v154
	v_mul_f32_e32 v155, 0x437f0000, v155
	v_cvt_pk_u8_f32 v150, v150, 0, 0
	v_max_f32_e32 v155, 1.0, v155
	v_mul_f32_e32 v165, 0x437f0000, v165
	v_cvt_pk_u8_f32 v150, v154, 1, v150
	v_max_f32_e32 v165, 1.0, v165
	v_cvt_pk_u8_f32 v150, v155, 2, v150
	v_cvt_pk_u8_f32 v154, v165, 3, v150
	v_mul_f32_e32 v150, v90, v164
	v_mul_f32_e32 v150, 0xbfb8aa3b, v150
	v_mul_f32_e32 v155, v91, v164
	v_exp_f32_e32 v150, v150
	v_mul_f32_e32 v155, 0xbfb8aa3b, v155
	v_mul_f32_e32 v165, v92, v164
	v_exp_f32_e32 v155, v155
	v_mul_f32_e32 v165, 0xbfb8aa3b, v165
	v_mul_f32_e32 v166, v93, v164
	v_exp_f32_e32 v165, v165
	v_mul_f32_e32 v166, 0xbfb8aa3b, v166
	v_exp_f32_e32 v166, v166
	v_add_f32_e32 v150, 1.0, v150
	v_rcp_f32_e32 v150, v150
	v_add_f32_e32 v155, 1.0, v155
	v_rcp_f32_e32 v155, v155
	v_add_f32_e32 v165, 1.0, v165
	v_rcp_f32_e32 v165, v165
	v_add_f32_e32 v166, 1.0, v166
	v_rcp_f32_e32 v166, v166
	v_mul_f32_e32 v150, 0x437f0000, v150
	v_max_f32_e32 v150, 1.0, v150
	v_mul_f32_e32 v155, 0x437f0000, v155
	v_max_f32_e32 v155, 1.0, v155
	v_mul_f32_e32 v165, 0x437f0000, v165
	v_cvt_pk_u8_f32 v150, v150, 0, 0
	v_max_f32_e32 v165, 1.0, v165
	v_mul_f32_e32 v166, 0x437f0000, v166
	v_cvt_pk_u8_f32 v150, v155, 1, v150
	v_max_f32_e32 v166, 1.0, v166
	v_cvt_pk_u8_f32 v150, v165, 2, v150
	v_cvt_pk_u8_f32 v155, v166, 3, v150
	v_mul_f32_e32 v150, v86, v164
	global_store_dwordx2 v[152:153], v[154:155], off nt
	v_mul_f32_e32 v150, 0xbfb8aa3b, v150
	v_mul_f32_e32 v154, v87, v164
	v_exp_f32_e32 v150, v150
	v_mul_f32_e32 v154, 0xbfb8aa3b, v154
	v_mul_f32_e32 v155, v88, v164
	v_exp_f32_e32 v154, v154
	v_mul_f32_e32 v155, 0xbfb8aa3b, v155
	v_mul_f32_e32 v165, v89, v164
	v_exp_f32_e32 v155, v155
	v_mul_f32_e32 v165, 0xbfb8aa3b, v165
	v_exp_f32_e32 v165, v165
	v_add_f32_e32 v150, 1.0, v150
	v_rcp_f32_e32 v150, v150
	v_add_f32_e32 v154, 1.0, v154
	v_rcp_f32_e32 v154, v154
	v_add_f32_e32 v155, 1.0, v155
	v_rcp_f32_e32 v155, v155
	v_add_f32_e32 v165, 1.0, v165
	v_rcp_f32_e32 v165, v165
	v_mul_f32_e32 v150, 0x437f0000, v150
	v_max_f32_e32 v150, 1.0, v150
	v_mul_f32_e32 v154, 0x437f0000, v154
	v_max_f32_e32 v154, 1.0, v154
	v_mul_f32_e32 v155, 0x437f0000, v155
	v_cvt_pk_u8_f32 v150, v150, 0, 0
	v_max_f32_e32 v155, 1.0, v155
	v_mul_f32_e32 v165, 0x437f0000, v165
	v_cvt_pk_u8_f32 v150, v154, 1, v150
	v_max_f32_e32 v165, 1.0, v165
	v_cvt_pk_u8_f32 v150, v155, 2, v150
	v_cvt_pk_u8_f32 v154, v165, 3, v150
	v_mul_f32_e32 v150, v82, v164
	v_mul_f32_e32 v150, 0xbfb8aa3b, v150
	v_mul_f32_e32 v155, v83, v164
	v_exp_f32_e32 v150, v150
	v_mul_f32_e32 v155, 0xbfb8aa3b, v155
	v_mul_f32_e32 v165, v84, v164
	v_exp_f32_e32 v155, v155
	v_mul_f32_e32 v165, 0xbfb8aa3b, v165
	v_mul_f32_e32 v164, v85, v164
	v_exp_f32_e32 v165, v165
	v_mul_f32_e32 v164, 0xbfb8aa3b, v164
	v_exp_f32_e32 v164, v164
	v_add_f32_e32 v150, 1.0, v150
	v_rcp_f32_e32 v150, v150
	v_add_f32_e32 v155, 1.0, v155
	v_rcp_f32_e32 v155, v155
	v_add_f32_e32 v165, 1.0, v165
	v_rcp_f32_e32 v165, v165
	v_add_f32_e32 v164, 1.0, v164
	v_rcp_f32_e32 v164, v164
	v_mul_f32_e32 v150, 0x437f0000, v150
	v_max_f32_e32 v150, 1.0, v150
	v_mul_f32_e32 v155, 0x437f0000, v155
	v_max_f32_e32 v155, 1.0, v155
	v_mul_f32_e32 v165, 0x437f0000, v165
	v_cvt_pk_u8_f32 v150, v150, 0, 0
	v_max_f32_e32 v165, 1.0, v165
	v_mul_f32_e32 v164, 0x437f0000, v164
	v_cvt_pk_u8_f32 v150, v155, 1, v150
	v_max_f32_e32 v164, 1.0, v164
	v_cvt_pk_u8_f32 v150, v165, 2, v150
	v_cvt_pk_u8_f32 v155, v164, 3, v150
	v_or_b32_e32 v150, 48, v146
	global_store_dwordx2 v[152:153], v[154:155], off offset:128 nt
	v_lshl_add_u32 v152, v150, 2, s0
	ds_read_b32 v164, v152
	v_mad_i64_i32 v[152:153], s[0:1], v150, s88, v[148:149]
	v_lshl_add_u64 v[152:153], v[152:153], 0, v[140:141]
	s_waitcnt lgkmcnt(0)
	v_mul_f32_e32 v150, v78, v164
	v_mul_f32_e32 v150, 0xbfb8aa3b, v150
	v_mul_f32_e32 v154, v79, v164
	v_exp_f32_e32 v150, v150
	v_mul_f32_e32 v154, 0xbfb8aa3b, v154
	v_mul_f32_e32 v155, v80, v164
	v_exp_f32_e32 v154, v154
	v_mul_f32_e32 v155, 0xbfb8aa3b, v155
	v_mul_f32_e32 v165, v81, v164
	v_exp_f32_e32 v155, v155
	v_mul_f32_e32 v165, 0xbfb8aa3b, v165
	v_exp_f32_e32 v165, v165
	v_add_f32_e32 v150, 1.0, v150
	v_rcp_f32_e32 v150, v150
	v_add_f32_e32 v154, 1.0, v154
	v_rcp_f32_e32 v154, v154
	v_add_f32_e32 v155, 1.0, v155
	v_rcp_f32_e32 v155, v155
	v_add_f32_e32 v165, 1.0, v165
	v_rcp_f32_e32 v165, v165
	v_mul_f32_e32 v150, 0x437f0000, v150
	v_max_f32_e32 v150, 1.0, v150
	v_mul_f32_e32 v154, 0x437f0000, v154
	v_max_f32_e32 v154, 1.0, v154
	v_mul_f32_e32 v155, 0x437f0000, v155
	v_cvt_pk_u8_f32 v150, v150, 0, 0
	v_max_f32_e32 v155, 1.0, v155
	v_mul_f32_e32 v165, 0x437f0000, v165
	v_cvt_pk_u8_f32 v150, v154, 1, v150
	v_max_f32_e32 v165, 1.0, v165
	v_cvt_pk_u8_f32 v150, v155, 2, v150
	v_cvt_pk_u8_f32 v154, v165, 3, v150
	v_mul_f32_e32 v150, v74, v164
	v_mul_f32_e32 v150, 0xbfb8aa3b, v150
	v_mul_f32_e32 v155, v75, v164
	v_exp_f32_e32 v150, v150
	v_mul_f32_e32 v155, 0xbfb8aa3b, v155
	v_mul_f32_e32 v165, v76, v164
	v_exp_f32_e32 v155, v155
	v_mul_f32_e32 v165, 0xbfb8aa3b, v165
	v_mul_f32_e32 v166, v77, v164
	v_exp_f32_e32 v165, v165
	v_mul_f32_e32 v166, 0xbfb8aa3b, v166
	v_exp_f32_e32 v166, v166
	v_add_f32_e32 v150, 1.0, v150
	v_rcp_f32_e32 v150, v150
	v_add_f32_e32 v155, 1.0, v155
	v_rcp_f32_e32 v155, v155
	v_add_f32_e32 v165, 1.0, v165
	v_rcp_f32_e32 v165, v165
	v_add_f32_e32 v166, 1.0, v166
	v_rcp_f32_e32 v166, v166
	v_mul_f32_e32 v150, 0x437f0000, v150
	v_max_f32_e32 v150, 1.0, v150
	v_mul_f32_e32 v155, 0x437f0000, v155
	v_max_f32_e32 v155, 1.0, v155
	v_mul_f32_e32 v165, 0x437f0000, v165
	v_cvt_pk_u8_f32 v150, v150, 0, 0
	v_max_f32_e32 v165, 1.0, v165
	v_mul_f32_e32 v166, 0x437f0000, v166
	v_cvt_pk_u8_f32 v150, v155, 1, v150
	v_max_f32_e32 v166, 1.0, v166
	v_cvt_pk_u8_f32 v150, v165, 2, v150
	v_cvt_pk_u8_f32 v155, v166, 3, v150
	v_mul_f32_e32 v150, v70, v164
	global_store_dwordx2 v[152:153], v[154:155], off nt
	v_mul_f32_e32 v150, 0xbfb8aa3b, v150
	v_mul_f32_e32 v154, v71, v164
	v_exp_f32_e32 v150, v150
	v_mul_f32_e32 v154, 0xbfb8aa3b, v154
	v_mul_f32_e32 v155, v72, v164
	v_exp_f32_e32 v154, v154
	v_mul_f32_e32 v155, 0xbfb8aa3b, v155
	v_mul_f32_e32 v165, v73, v164
	v_exp_f32_e32 v155, v155
	v_mul_f32_e32 v165, 0xbfb8aa3b, v165
	v_exp_f32_e32 v165, v165
	v_add_f32_e32 v150, 1.0, v150
	v_rcp_f32_e32 v150, v150
	v_add_f32_e32 v154, 1.0, v154
	v_rcp_f32_e32 v154, v154
	v_add_f32_e32 v155, 1.0, v155
	v_rcp_f32_e32 v155, v155
	v_add_f32_e32 v165, 1.0, v165
	v_rcp_f32_e32 v165, v165
	v_mul_f32_e32 v150, 0x437f0000, v150
	v_max_f32_e32 v150, 1.0, v150
	v_mul_f32_e32 v154, 0x437f0000, v154
	v_max_f32_e32 v154, 1.0, v154
	v_mul_f32_e32 v155, 0x437f0000, v155
	v_cvt_pk_u8_f32 v150, v150, 0, 0
	v_max_f32_e32 v155, 1.0, v155
	v_mul_f32_e32 v165, 0x437f0000, v165
	v_cvt_pk_u8_f32 v150, v154, 1, v150
	v_max_f32_e32 v165, 1.0, v165
	v_cvt_pk_u8_f32 v150, v155, 2, v150
	v_cvt_pk_u8_f32 v154, v165, 3, v150
	v_mul_f32_e32 v150, v66, v164
	v_mul_f32_e32 v150, 0xbfb8aa3b, v150
	v_mul_f32_e32 v155, v67, v164
	v_exp_f32_e32 v150, v150
	v_mul_f32_e32 v155, 0xbfb8aa3b, v155
	v_mul_f32_e32 v165, v68, v164
	v_exp_f32_e32 v155, v155
	v_mul_f32_e32 v165, 0xbfb8aa3b, v165
	v_mul_f32_e32 v164, v69, v164
	v_exp_f32_e32 v165, v165
	v_mul_f32_e32 v164, 0xbfb8aa3b, v164
	v_exp_f32_e32 v164, v164
	v_add_f32_e32 v150, 1.0, v150
	v_rcp_f32_e32 v150, v150
	v_add_f32_e32 v155, 1.0, v155
	v_rcp_f32_e32 v155, v155
	v_add_f32_e32 v165, 1.0, v165
	v_rcp_f32_e32 v165, v165
	v_add_f32_e32 v164, 1.0, v164
	v_rcp_f32_e32 v164, v164
	v_mul_f32_e32 v150, 0x437f0000, v150
	v_max_f32_e32 v150, 1.0, v150
	v_mul_f32_e32 v155, 0x437f0000, v155
	v_max_f32_e32 v155, 1.0, v155
	v_mul_f32_e32 v165, 0x437f0000, v165
	v_cvt_pk_u8_f32 v150, v150, 0, 0
	v_max_f32_e32 v165, 1.0, v165
	v_mul_f32_e32 v164, 0x437f0000, v164
	v_cvt_pk_u8_f32 v150, v155, 1, v150
	v_max_f32_e32 v164, 1.0, v164
	v_cvt_pk_u8_f32 v150, v165, 2, v150
	v_cvt_pk_u8_f32 v155, v164, 3, v150
	v_add_u32_e32 v150, 0x80, v146
	global_store_dwordx2 v[152:153], v[154:155], off offset:128 nt
	v_mad_i64_i32 v[152:153], s[0:1], v150, s88, v[148:149]
	v_mul_f32_e32 v150, v62, v151
	v_mul_f32_e32 v150, 0xbfb8aa3b, v150
	v_mul_f32_e32 v154, v63, v151
	v_exp_f32_e32 v150, v150
	v_mul_f32_e32 v154, 0xbfb8aa3b, v154
	v_mul_f32_e32 v155, v64, v151
	v_exp_f32_e32 v154, v154
	v_mul_f32_e32 v155, 0xbfb8aa3b, v155
	v_mul_f32_e32 v164, v65, v151
	v_exp_f32_e32 v155, v155
	v_mul_f32_e32 v164, 0xbfb8aa3b, v164
	v_exp_f32_e32 v164, v164
	v_add_f32_e32 v150, 1.0, v150
	v_rcp_f32_e32 v150, v150
	v_add_f32_e32 v154, 1.0, v154
	v_rcp_f32_e32 v154, v154
	v_add_f32_e32 v155, 1.0, v155
	v_rcp_f32_e32 v155, v155
	v_add_f32_e32 v164, 1.0, v164
	v_rcp_f32_e32 v164, v164
	v_mul_f32_e32 v150, 0x437f0000, v150
	v_max_f32_e32 v150, 1.0, v150
	v_mul_f32_e32 v154, 0x437f0000, v154
	v_max_f32_e32 v154, 1.0, v154
	v_mul_f32_e32 v155, 0x437f0000, v155
	v_cvt_pk_u8_f32 v150, v150, 0, 0
	v_max_f32_e32 v155, 1.0, v155
	v_mul_f32_e32 v164, 0x437f0000, v164
	v_cvt_pk_u8_f32 v150, v154, 1, v150
	v_max_f32_e32 v164, 1.0, v164
	v_cvt_pk_u8_f32 v150, v155, 2, v150
	v_cvt_pk_u8_f32 v154, v164, 3, v150
	v_mul_f32_e32 v150, v58, v151
	v_mul_f32_e32 v150, 0xbfb8aa3b, v150
	v_mul_f32_e32 v155, v59, v151
	v_exp_f32_e32 v150, v150
	v_mul_f32_e32 v155, 0xbfb8aa3b, v155
	v_mul_f32_e32 v164, v60, v151
	v_exp_f32_e32 v155, v155
	v_mul_f32_e32 v164, 0xbfb8aa3b, v164
	v_mul_f32_e32 v165, v61, v151
	v_exp_f32_e32 v164, v164
	v_mul_f32_e32 v165, 0xbfb8aa3b, v165
	v_exp_f32_e32 v165, v165
	v_add_f32_e32 v150, 1.0, v150
	v_rcp_f32_e32 v150, v150
	v_add_f32_e32 v155, 1.0, v155
	v_rcp_f32_e32 v155, v155
	v_add_f32_e32 v164, 1.0, v164
	v_rcp_f32_e32 v164, v164
	v_add_f32_e32 v165, 1.0, v165
	v_rcp_f32_e32 v165, v165
	v_mul_f32_e32 v150, 0x437f0000, v150
	v_max_f32_e32 v150, 1.0, v150
	v_mul_f32_e32 v155, 0x437f0000, v155
	v_max_f32_e32 v155, 1.0, v155
	v_mul_f32_e32 v164, 0x437f0000, v164
	v_cvt_pk_u8_f32 v150, v150, 0, 0
	v_max_f32_e32 v164, 1.0, v164
	v_mul_f32_e32 v165, 0x437f0000, v165
	v_cvt_pk_u8_f32 v150, v155, 1, v150
	v_max_f32_e32 v165, 1.0, v165
	v_cvt_pk_u8_f32 v150, v164, 2, v150
	v_lshl_add_u64 v[152:153], v[152:153], 0, v[140:141]
	v_cvt_pk_u8_f32 v155, v165, 3, v150
	v_mul_f32_e32 v150, v54, v151
	global_store_dwordx2 v[152:153], v[154:155], off nt
	v_mul_f32_e32 v150, 0xbfb8aa3b, v150
	v_mul_f32_e32 v154, v55, v151
	v_exp_f32_e32 v150, v150
	v_mul_f32_e32 v154, 0xbfb8aa3b, v154
	v_mul_f32_e32 v155, v56, v151
	v_exp_f32_e32 v154, v154
	v_mul_f32_e32 v155, 0xbfb8aa3b, v155
	v_mul_f32_e32 v164, v57, v151
	v_exp_f32_e32 v155, v155
	v_mul_f32_e32 v164, 0xbfb8aa3b, v164
	v_exp_f32_e32 v164, v164
	v_add_f32_e32 v150, 1.0, v150
	v_rcp_f32_e32 v150, v150
	v_add_f32_e32 v154, 1.0, v154
	v_rcp_f32_e32 v154, v154
	v_add_f32_e32 v155, 1.0, v155
	v_rcp_f32_e32 v155, v155
	v_add_f32_e32 v164, 1.0, v164
	v_rcp_f32_e32 v164, v164
	v_mul_f32_e32 v150, 0x437f0000, v150
	v_max_f32_e32 v150, 1.0, v150
	v_mul_f32_e32 v154, 0x437f0000, v154
	v_max_f32_e32 v154, 1.0, v154
	v_mul_f32_e32 v155, 0x437f0000, v155
	v_cvt_pk_u8_f32 v150, v150, 0, 0
	v_max_f32_e32 v155, 1.0, v155
	v_mul_f32_e32 v164, 0x437f0000, v164
	v_cvt_pk_u8_f32 v150, v154, 1, v150
	v_mul_f32_e32 v154, v50, v151
	v_max_f32_e32 v164, 1.0, v164
	v_cvt_pk_u8_f32 v150, v155, 2, v150
	v_mul_f32_e32 v154, 0xbfb8aa3b, v154
	v_mul_f32_e32 v155, v51, v151
	v_cvt_pk_u8_f32 v150, v164, 3, v150
	v_exp_f32_e32 v154, v154
	v_mul_f32_e32 v155, 0xbfb8aa3b, v155
	v_mul_f32_e32 v164, v52, v151
	v_exp_f32_e32 v155, v155
	v_mul_f32_e32 v164, 0xbfb8aa3b, v164
	v_mul_f32_e32 v151, v53, v151
	v_exp_f32_e32 v164, v164
	v_mul_f32_e32 v151, 0xbfb8aa3b, v151
	v_exp_f32_e32 v151, v151
	v_add_f32_e32 v154, 1.0, v154
	v_rcp_f32_e32 v154, v154
	v_add_f32_e32 v155, 1.0, v155
	v_rcp_f32_e32 v155, v155
	v_add_f32_e32 v164, 1.0, v164
	v_rcp_f32_e32 v164, v164
	v_add_f32_e32 v151, 1.0, v151
	v_rcp_f32_e32 v151, v151
	v_mul_f32_e32 v154, 0x437f0000, v154
	v_max_f32_e32 v154, 1.0, v154
	v_mul_f32_e32 v155, 0x437f0000, v155
	v_max_f32_e32 v155, 1.0, v155
	v_mul_f32_e32 v164, 0x437f0000, v164
	v_cvt_pk_u8_f32 v154, v154, 0, 0
	v_max_f32_e32 v164, 1.0, v164
	v_mul_f32_e32 v151, 0x437f0000, v151
	v_cvt_pk_u8_f32 v154, v155, 1, v154
	v_max_f32_e32 v151, 1.0, v151
	v_cvt_pk_u8_f32 v154, v164, 2, v154
	v_cvt_pk_u8_f32 v151, v151, 3, v154
	global_store_dwordx2 v[152:153], v[150:151], off offset:128 nt
	ds_read2_b32 v[150:151], v147 offset0:144 offset1:160
	v_add_u32_e32 v152, 0x90, v146
	v_mad_i64_i32 v[152:153], s[0:1], v152, s88, v[148:149]
	v_lshl_add_u64 v[152:153], v[152:153], 0, v[140:141]
	s_waitcnt lgkmcnt(0)
	v_mul_f32_e32 v154, v46, v150
	v_mul_f32_e32 v154, 0xbfb8aa3b, v154
	v_mul_f32_e32 v155, v47, v150
	v_exp_f32_e32 v154, v154
	v_mul_f32_e32 v155, 0xbfb8aa3b, v155
	v_mul_f32_e32 v164, v48, v150
	v_exp_f32_e32 v155, v155
	v_mul_f32_e32 v164, 0xbfb8aa3b, v164
	v_mul_f32_e32 v165, v49, v150
	v_exp_f32_e32 v164, v164
	v_mul_f32_e32 v165, 0xbfb8aa3b, v165
	v_exp_f32_e32 v165, v165
	v_add_f32_e32 v154, 1.0, v154
	v_rcp_f32_e32 v154, v154
	v_add_f32_e32 v155, 1.0, v155
	v_rcp_f32_e32 v155, v155
	v_add_f32_e32 v164, 1.0, v164
	v_rcp_f32_e32 v164, v164
	v_add_f32_e32 v165, 1.0, v165
	v_rcp_f32_e32 v165, v165
	v_mul_f32_e32 v154, 0x437f0000, v154
	v_max_f32_e32 v154, 1.0, v154
	v_mul_f32_e32 v155, 0x437f0000, v155
	v_max_f32_e32 v155, 1.0, v155
	v_mul_f32_e32 v164, 0x437f0000, v164
	v_cvt_pk_u8_f32 v154, v154, 0, 0
	v_max_f32_e32 v164, 1.0, v164
	v_mul_f32_e32 v165, 0x437f0000, v165
	v_cvt_pk_u8_f32 v154, v155, 1, v154
	v_mul_f32_e32 v155, v42, v150
	v_max_f32_e32 v165, 1.0, v165
	v_cvt_pk_u8_f32 v154, v164, 2, v154
	v_mul_f32_e32 v155, 0xbfb8aa3b, v155
	v_mul_f32_e32 v164, v43, v150
	v_cvt_pk_u8_f32 v154, v165, 3, v154
	v_exp_f32_e32 v155, v155
	v_mul_f32_e32 v164, 0xbfb8aa3b, v164
	v_mul_f32_e32 v165, v44, v150
	v_exp_f32_e32 v164, v164
	v_mul_f32_e32 v165, 0xbfb8aa3b, v165
	v_mul_f32_e32 v166, v45, v150
	v_exp_f32_e32 v165, v165
	v_mul_f32_e32 v166, 0xbfb8aa3b, v166
	v_exp_f32_e32 v166, v166
	v_add_f32_e32 v155, 1.0, v155
	v_rcp_f32_e32 v155, v155
	v_add_f32_e32 v164, 1.0, v164
	v_rcp_f32_e32 v164, v164
	v_add_f32_e32 v165, 1.0, v165
	v_rcp_f32_e32 v165, v165
	v_add_f32_e32 v166, 1.0, v166
	v_rcp_f32_e32 v166, v166
	v_mul_f32_e32 v155, 0x437f0000, v155
	v_max_f32_e32 v155, 1.0, v155
	v_mul_f32_e32 v164, 0x437f0000, v164
	v_max_f32_e32 v164, 1.0, v164
	v_mul_f32_e32 v165, 0x437f0000, v165
	v_cvt_pk_u8_f32 v155, v155, 0, 0
	v_max_f32_e32 v165, 1.0, v165
	v_mul_f32_e32 v166, 0x437f0000, v166
	v_cvt_pk_u8_f32 v155, v164, 1, v155
	v_max_f32_e32 v166, 1.0, v166
	v_cvt_pk_u8_f32 v155, v165, 2, v155
	v_cvt_pk_u8_f32 v155, v166, 3, v155
	global_store_dwordx2 v[152:153], v[154:155], off nt
	v_mul_f32_e32 v154, v38, v150
	v_mul_f32_e32 v154, 0xbfb8aa3b, v154
	v_mul_f32_e32 v155, v39, v150
	v_exp_f32_e32 v154, v154
	v_mul_f32_e32 v155, 0xbfb8aa3b, v155
	v_mul_f32_e32 v164, v40, v150
	v_exp_f32_e32 v155, v155
	v_mul_f32_e32 v164, 0xbfb8aa3b, v164
	v_mul_f32_e32 v165, v41, v150
	v_exp_f32_e32 v164, v164
	v_mul_f32_e32 v165, 0xbfb8aa3b, v165
	v_exp_f32_e32 v165, v165
	v_add_f32_e32 v154, 1.0, v154
	v_rcp_f32_e32 v154, v154
	v_add_f32_e32 v155, 1.0, v155
	v_rcp_f32_e32 v155, v155
	v_add_f32_e32 v164, 1.0, v164
	v_rcp_f32_e32 v164, v164
	v_add_f32_e32 v165, 1.0, v165
	v_rcp_f32_e32 v165, v165
	v_mul_f32_e32 v154, 0x437f0000, v154
	v_max_f32_e32 v154, 1.0, v154
	v_mul_f32_e32 v155, 0x437f0000, v155
	v_max_f32_e32 v155, 1.0, v155
	v_mul_f32_e32 v164, 0x437f0000, v164
	v_cvt_pk_u8_f32 v154, v154, 0, 0
	v_max_f32_e32 v164, 1.0, v164
	v_mul_f32_e32 v165, 0x437f0000, v165
	v_cvt_pk_u8_f32 v154, v155, 1, v154
	v_mul_f32_e32 v155, v34, v150
	v_max_f32_e32 v165, 1.0, v165
	v_cvt_pk_u8_f32 v154, v164, 2, v154
	v_mul_f32_e32 v155, 0xbfb8aa3b, v155
	v_mul_f32_e32 v164, v35, v150
	v_cvt_pk_u8_f32 v154, v165, 3, v154
	v_exp_f32_e32 v155, v155
	v_mul_f32_e32 v164, 0xbfb8aa3b, v164
	v_mul_f32_e32 v165, v36, v150
	v_exp_f32_e32 v164, v164
	v_mul_f32_e32 v165, 0xbfb8aa3b, v165
	v_mul_f32_e32 v150, v37, v150
	v_exp_f32_e32 v165, v165
	v_mul_f32_e32 v150, 0xbfb8aa3b, v150
	v_exp_f32_e32 v150, v150
	v_add_f32_e32 v155, 1.0, v155
	v_rcp_f32_e32 v155, v155
	v_add_f32_e32 v164, 1.0, v164
	v_rcp_f32_e32 v164, v164
	v_add_f32_e32 v165, 1.0, v165
	v_rcp_f32_e32 v165, v165
	v_add_f32_e32 v150, 1.0, v150
	v_rcp_f32_e32 v150, v150
	v_mul_f32_e32 v155, 0x437f0000, v155
	v_max_f32_e32 v155, 1.0, v155
	v_mul_f32_e32 v164, 0x437f0000, v164
	v_max_f32_e32 v164, 1.0, v164
	v_mul_f32_e32 v165, 0x437f0000, v165
	v_cvt_pk_u8_f32 v155, v155, 0, 0
	v_max_f32_e32 v165, 1.0, v165
	v_mul_f32_e32 v150, 0x437f0000, v150
	v_cvt_pk_u8_f32 v155, v164, 1, v155
	v_max_f32_e32 v150, 1.0, v150
	v_cvt_pk_u8_f32 v155, v165, 2, v155
	v_cvt_pk_u8_f32 v155, v150, 3, v155
	v_add_u32_e32 v150, 0xa0, v146
	global_store_dwordx2 v[152:153], v[154:155], off offset:128 nt
	v_mad_i64_i32 v[152:153], s[0:1], v150, s88, v[148:149]
	v_mul_f32_e32 v150, v30, v151
	v_mul_f32_e32 v150, 0xbfb8aa3b, v150
	v_mul_f32_e32 v154, v31, v151
	v_exp_f32_e32 v150, v150
	v_mul_f32_e32 v154, 0xbfb8aa3b, v154
	v_mul_f32_e32 v155, v32, v151
	v_exp_f32_e32 v154, v154
	v_mul_f32_e32 v155, 0xbfb8aa3b, v155
	v_mul_f32_e32 v164, v33, v151
	v_exp_f32_e32 v155, v155
	v_mul_f32_e32 v164, 0xbfb8aa3b, v164
	v_exp_f32_e32 v164, v164
	v_add_f32_e32 v150, 1.0, v150
	v_rcp_f32_e32 v150, v150
	v_add_f32_e32 v154, 1.0, v154
	v_rcp_f32_e32 v154, v154
	v_add_f32_e32 v155, 1.0, v155
	v_rcp_f32_e32 v155, v155
	v_add_f32_e32 v164, 1.0, v164
	v_rcp_f32_e32 v164, v164
	v_mul_f32_e32 v150, 0x437f0000, v150
	v_max_f32_e32 v150, 1.0, v150
	v_mul_f32_e32 v154, 0x437f0000, v154
	v_max_f32_e32 v154, 1.0, v154
	v_mul_f32_e32 v155, 0x437f0000, v155
	v_cvt_pk_u8_f32 v150, v150, 0, 0
	v_max_f32_e32 v155, 1.0, v155
	v_mul_f32_e32 v164, 0x437f0000, v164
	v_cvt_pk_u8_f32 v150, v154, 1, v150
	v_max_f32_e32 v164, 1.0, v164
	v_cvt_pk_u8_f32 v150, v155, 2, v150
	v_cvt_pk_u8_f32 v154, v164, 3, v150
	v_mul_f32_e32 v150, v26, v151
	v_mul_f32_e32 v150, 0xbfb8aa3b, v150
	v_mul_f32_e32 v155, v27, v151
	v_exp_f32_e32 v150, v150
	v_mul_f32_e32 v155, 0xbfb8aa3b, v155
	v_mul_f32_e32 v164, v28, v151
	v_exp_f32_e32 v155, v155
	v_mul_f32_e32 v164, 0xbfb8aa3b, v164
	v_mul_f32_e32 v165, v29, v151
	v_exp_f32_e32 v164, v164
	v_mul_f32_e32 v165, 0xbfb8aa3b, v165
	v_exp_f32_e32 v165, v165
	v_add_f32_e32 v150, 1.0, v150
	v_rcp_f32_e32 v150, v150
	v_add_f32_e32 v155, 1.0, v155
	v_rcp_f32_e32 v155, v155
	v_add_f32_e32 v164, 1.0, v164
	v_rcp_f32_e32 v164, v164
	v_add_f32_e32 v165, 1.0, v165
	v_rcp_f32_e32 v165, v165
	v_mul_f32_e32 v150, 0x437f0000, v150
	v_max_f32_e32 v150, 1.0, v150
	v_mul_f32_e32 v155, 0x437f0000, v155
	v_max_f32_e32 v155, 1.0, v155
	v_mul_f32_e32 v164, 0x437f0000, v164
	v_cvt_pk_u8_f32 v150, v150, 0, 0
	v_max_f32_e32 v164, 1.0, v164
	v_mul_f32_e32 v165, 0x437f0000, v165
	v_cvt_pk_u8_f32 v150, v155, 1, v150
	v_max_f32_e32 v165, 1.0, v165
	v_cvt_pk_u8_f32 v150, v164, 2, v150
	v_lshl_add_u64 v[152:153], v[152:153], 0, v[140:141]
	v_cvt_pk_u8_f32 v155, v165, 3, v150
	v_mul_f32_e32 v150, v22, v151
	global_store_dwordx2 v[152:153], v[154:155], off nt
	v_mul_f32_e32 v150, 0xbfb8aa3b, v150
	v_mul_f32_e32 v154, v23, v151
	v_exp_f32_e32 v150, v150
	v_mul_f32_e32 v154, 0xbfb8aa3b, v154
	v_mul_f32_e32 v155, v24, v151
	v_exp_f32_e32 v154, v154
	v_mul_f32_e32 v155, 0xbfb8aa3b, v155
	v_mul_f32_e32 v164, v25, v151
	v_exp_f32_e32 v155, v155
	v_mul_f32_e32 v164, 0xbfb8aa3b, v164
	v_exp_f32_e32 v164, v164
	v_add_f32_e32 v150, 1.0, v150
	v_rcp_f32_e32 v150, v150
	v_add_f32_e32 v154, 1.0, v154
	v_rcp_f32_e32 v154, v154
	v_add_f32_e32 v155, 1.0, v155
	v_rcp_f32_e32 v155, v155
	v_add_f32_e32 v164, 1.0, v164
	v_rcp_f32_e32 v164, v164
	v_mul_f32_e32 v150, 0x437f0000, v150
	v_max_f32_e32 v150, 1.0, v150
	v_mul_f32_e32 v154, 0x437f0000, v154
	v_max_f32_e32 v154, 1.0, v154
	v_mul_f32_e32 v155, 0x437f0000, v155
	v_cvt_pk_u8_f32 v150, v150, 0, 0
	v_max_f32_e32 v155, 1.0, v155
	v_mul_f32_e32 v164, 0x437f0000, v164
	v_cvt_pk_u8_f32 v150, v154, 1, v150
	v_mul_f32_e32 v154, v18, v151
	v_max_f32_e32 v164, 1.0, v164
	v_cvt_pk_u8_f32 v150, v155, 2, v150
	v_mul_f32_e32 v154, 0xbfb8aa3b, v154
	v_mul_f32_e32 v155, v19, v151
	v_cvt_pk_u8_f32 v150, v164, 3, v150
	v_exp_f32_e32 v154, v154
	v_mul_f32_e32 v155, 0xbfb8aa3b, v155
	v_mul_f32_e32 v164, v20, v151
	v_exp_f32_e32 v155, v155
	v_mul_f32_e32 v164, 0xbfb8aa3b, v164
	v_mul_f32_e32 v151, v21, v151
	v_exp_f32_e32 v164, v164
	v_mul_f32_e32 v151, 0xbfb8aa3b, v151
	v_exp_f32_e32 v151, v151
	v_add_f32_e32 v154, 1.0, v154
	v_rcp_f32_e32 v154, v154
	v_add_f32_e32 v155, 1.0, v155
	v_rcp_f32_e32 v155, v155
	v_add_f32_e32 v164, 1.0, v164
	v_rcp_f32_e32 v164, v164
	v_add_f32_e32 v151, 1.0, v151
	v_rcp_f32_e32 v151, v151
	v_mul_f32_e32 v154, 0x437f0000, v154
	v_max_f32_e32 v154, 1.0, v154
	v_mul_f32_e32 v155, 0x437f0000, v155
	v_max_f32_e32 v155, 1.0, v155
	v_mul_f32_e32 v164, 0x437f0000, v164
	v_cvt_pk_u8_f32 v154, v154, 0, 0
	v_max_f32_e32 v164, 1.0, v164
	v_mul_f32_e32 v151, 0x437f0000, v151
	v_cvt_pk_u8_f32 v154, v155, 1, v154
	ds_read_b32 v147, v147 offset:704
	v_max_f32_e32 v151, 1.0, v151
	v_cvt_pk_u8_f32 v154, v164, 2, v154
	v_cvt_pk_u8_f32 v151, v151, 3, v154
	global_store_dwordx2 v[152:153], v[150:151], off offset:128 nt
	v_add_u32_e32 v150, 0xb0, v146
	v_mad_i64_i32 v[148:149], s[0:1], v150, s88, v[148:149]
	v_lshl_add_u64 v[148:149], v[148:149], 0, v[140:141]
	s_waitcnt lgkmcnt(0)
	v_mul_f32_e32 v140, v14, v147
	v_mul_f32_e32 v140, 0xbfb8aa3b, v140
	v_mul_f32_e32 v150, v15, v147
	v_exp_f32_e32 v140, v140
	v_mul_f32_e32 v150, 0xbfb8aa3b, v150
	v_mul_f32_e32 v151, v16, v147
	v_exp_f32_e32 v150, v150
	v_mul_f32_e32 v151, 0xbfb8aa3b, v151
	v_mul_f32_e32 v152, v17, v147
	v_exp_f32_e32 v151, v151
	v_mul_f32_e32 v152, 0xbfb8aa3b, v152
	v_exp_f32_e32 v152, v152
	v_add_f32_e32 v140, 1.0, v140
	v_rcp_f32_e32 v140, v140
	v_add_f32_e32 v150, 1.0, v150
	v_rcp_f32_e32 v150, v150
	v_add_f32_e32 v151, 1.0, v151
	v_rcp_f32_e32 v151, v151
	v_add_f32_e32 v152, 1.0, v152
	v_rcp_f32_e32 v152, v152
	v_mul_f32_e32 v140, 0x437f0000, v140
	v_max_f32_e32 v140, 1.0, v140
	v_mul_f32_e32 v150, 0x437f0000, v150
	v_max_f32_e32 v150, 1.0, v150
	v_mul_f32_e32 v151, 0x437f0000, v151
	v_cvt_pk_u8_f32 v140, v140, 0, 0
	v_max_f32_e32 v151, 1.0, v151
	v_mul_f32_e32 v152, 0x437f0000, v152
	v_cvt_pk_u8_f32 v140, v150, 1, v140
	v_max_f32_e32 v152, 1.0, v152
	v_cvt_pk_u8_f32 v140, v151, 2, v140
	v_cvt_pk_u8_f32 v150, v152, 3, v140
	v_mul_f32_e32 v140, v10, v147
	v_mul_f32_e32 v140, 0xbfb8aa3b, v140
	v_mul_f32_e32 v151, v11, v147
	v_exp_f32_e32 v140, v140
	v_mul_f32_e32 v151, 0xbfb8aa3b, v151
	v_mul_f32_e32 v152, v12, v147
	v_exp_f32_e32 v151, v151
	v_mul_f32_e32 v152, 0xbfb8aa3b, v152
	v_mul_f32_e32 v153, v13, v147
	v_exp_f32_e32 v152, v152
	v_mul_f32_e32 v153, 0xbfb8aa3b, v153
	v_exp_f32_e32 v153, v153
	v_add_f32_e32 v140, 1.0, v140
	v_rcp_f32_e32 v140, v140
	v_add_f32_e32 v151, 1.0, v151
	v_rcp_f32_e32 v151, v151
	v_add_f32_e32 v152, 1.0, v152
	v_rcp_f32_e32 v152, v152
	v_add_f32_e32 v153, 1.0, v153
	v_rcp_f32_e32 v153, v153
	v_mul_f32_e32 v140, 0x437f0000, v140
	v_max_f32_e32 v140, 1.0, v140
	v_mul_f32_e32 v151, 0x437f0000, v151
	v_max_f32_e32 v151, 1.0, v151
	v_mul_f32_e32 v152, 0x437f0000, v152
	v_cvt_pk_u8_f32 v140, v140, 0, 0
	v_max_f32_e32 v152, 1.0, v152
	v_mul_f32_e32 v153, 0x437f0000, v153
	v_cvt_pk_u8_f32 v140, v151, 1, v140
	v_max_f32_e32 v153, 1.0, v153
	v_cvt_pk_u8_f32 v140, v152, 2, v140
	v_cvt_pk_u8_f32 v151, v153, 3, v140
	v_mul_f32_e32 v140, v6, v147
	global_store_dwordx2 v[148:149], v[150:151], off nt
	v_mul_f32_e32 v140, 0xbfb8aa3b, v140
	v_mul_f32_e32 v150, v7, v147
	v_exp_f32_e32 v140, v140
	v_mul_f32_e32 v150, 0xbfb8aa3b, v150
	v_mul_f32_e32 v151, v8, v147
	v_exp_f32_e32 v150, v150
	v_mul_f32_e32 v151, 0xbfb8aa3b, v151
	v_mul_f32_e32 v152, v9, v147
	v_exp_f32_e32 v151, v151
	v_mul_f32_e32 v152, 0xbfb8aa3b, v152
	v_exp_f32_e32 v152, v152
	v_add_f32_e32 v140, 1.0, v140
	v_rcp_f32_e32 v140, v140
	v_add_f32_e32 v150, 1.0, v150
	v_rcp_f32_e32 v150, v150
	v_add_f32_e32 v151, 1.0, v151
	v_rcp_f32_e32 v151, v151
	v_add_f32_e32 v152, 1.0, v152
	v_rcp_f32_e32 v152, v152
	v_mul_f32_e32 v140, 0x437f0000, v140
	v_max_f32_e32 v140, 1.0, v140
	v_mul_f32_e32 v150, 0x437f0000, v150
	v_max_f32_e32 v150, 1.0, v150
	v_mul_f32_e32 v151, 0x437f0000, v151
	v_cvt_pk_u8_f32 v140, v140, 0, 0
	v_max_f32_e32 v151, 1.0, v151
	v_mul_f32_e32 v152, 0x437f0000, v152
	v_cvt_pk_u8_f32 v140, v150, 1, v140
	v_max_f32_e32 v152, 1.0, v152
	v_cvt_pk_u8_f32 v140, v151, 2, v140
	v_cvt_pk_u8_f32 v150, v152, 3, v140
	v_mul_f32_e32 v140, v2, v147
	v_mul_f32_e32 v140, 0xbfb8aa3b, v140
	v_mul_f32_e32 v151, v3, v147
	v_exp_f32_e32 v140, v140
	v_mul_f32_e32 v151, 0xbfb8aa3b, v151
	v_mul_f32_e32 v152, v4, v147
	v_exp_f32_e32 v151, v151
	v_mul_f32_e32 v152, 0xbfb8aa3b, v152
	v_mul_f32_e32 v147, v5, v147
	v_exp_f32_e32 v152, v152
	v_mul_f32_e32 v147, 0xbfb8aa3b, v147
	v_exp_f32_e32 v147, v147
	v_add_f32_e32 v140, 1.0, v140
	v_rcp_f32_e32 v140, v140
	v_add_f32_e32 v151, 1.0, v151
	v_rcp_f32_e32 v151, v151
	v_add_f32_e32 v152, 1.0, v152
	v_rcp_f32_e32 v152, v152
	v_add_f32_e32 v147, 1.0, v147
	v_rcp_f32_e32 v147, v147
	v_mul_f32_e32 v140, 0x437f0000, v140
	v_max_f32_e32 v140, 1.0, v140
	v_mul_f32_e32 v151, 0x437f0000, v151
	v_max_f32_e32 v151, 1.0, v151
	v_mul_f32_e32 v152, 0x437f0000, v152
	v_cvt_pk_u8_f32 v140, v140, 0, 0
	v_max_f32_e32 v152, 1.0, v152
	v_mul_f32_e32 v147, 0x437f0000, v147
	v_cvt_pk_u8_f32 v140, v151, 1, v140
	v_max_f32_e32 v147, 1.0, v147
	v_cvt_pk_u8_f32 v140, v152, 2, v140
	v_cvt_pk_u8_f32 v151, v147, 3, v140
	global_store_dwordx2 v[148:149], v[150:151], off offset:128 nt
	s_mov_b64 s[0:1], 0
.LBB0_656:
	s_andn2_b64 vcc, exec, s[0:1]
	s_cbranch_vccnz .LBB0_658
	s_lshl_b32 s0, s5, 2
	s_add_i32 s0, s0, 0
	v_add_u32_e32 v140, s7, v159
	s_add_i32 s0, s0, 0x20000
	v_lshl_add_u64 v[152:153], v[140:141], 1, s[44:45]
	v_lshl_add_u32 v140, v146, 2, s0
	ds_read2st64_b32 v[150:151], v140 offset1:2
	v_ashrrev_i32_e32 v147, 31, v146
	v_lshlrev_b64 v[148:149], 11, v[146:147]
	v_lshl_add_u64 v[148:149], v[152:153], 0, v[148:149]
	s_waitcnt lgkmcnt(0)
	v_mul_f32_e32 v150, 0x3db8aa3b, v150
	v_pk_mul_f32 v[154:155], v[128:129], v[150:151] op_sel_hi:[1,0]
	v_pk_mul_f32 v[164:165], v[126:127], v[150:151] op_sel_hi:[1,0]
	v_pk_mul_f32 v[168:169], v[124:125], v[150:151] op_sel_hi:[1,0]
	v_pk_mul_f32 v[166:167], v[122:123], v[150:151] op_sel_hi:[1,0]
	v_cvt_pk_bf16_f32 v164, v164, v165
	v_cvt_pk_bf16_f32 v165, v154, v155
	v_cvt_pk_bf16_f32 v166, v166, v167
	v_cvt_pk_bf16_f32 v167, v168, v169
	global_store_dwordx4 v[148:149], v[164:167], off nt
	v_pk_mul_f32 v[154:155], v[120:121], v[150:151] op_sel_hi:[1,0]
	v_pk_mul_f32 v[168:169], v[116:117], v[150:151] op_sel_hi:[1,0]
	v_pk_mul_f32 v[164:165], v[118:119], v[150:151] op_sel_hi:[1,0]
	v_pk_mul_f32 v[166:167], v[114:115], v[150:151] op_sel_hi:[1,0]
	v_cvt_pk_bf16_f32 v164, v164, v165
	v_cvt_pk_bf16_f32 v165, v154, v155
	v_or_b32_e32 v154, 16, v146
	v_lshl_add_u32 v147, v154, 2, s0
	ds_read_b32 v147, v147
	v_cvt_pk_bf16_f32 v166, v166, v167
	v_cvt_pk_bf16_f32 v167, v168, v169
	v_ashrrev_i32_e32 v155, 31, v154
	global_store_dwordx4 v[148:149], v[164:167], off offset:256 nt
	s_waitcnt lgkmcnt(0)
	v_mul_f32_e32 v150, 0x3db8aa3b, v147
	v_lshlrev_b64 v[154:155], 11, v[154:155]
	v_pk_mul_f32 v[166:167], v[112:113], v[150:151] op_sel_hi:[1,0]
	v_pk_mul_f32 v[164:165], v[110:111], v[150:151] op_sel_hi:[1,0]
	v_pk_mul_f32 v[168:169], v[108:109], v[150:151] op_sel_hi:[1,0]
	v_pk_mul_f32 v[170:171], v[106:107], v[150:151] op_sel_hi:[1,0]
	v_lshl_add_u64 v[154:155], v[152:153], 0, v[154:155]
	v_cvt_pk_bf16_f32 v164, v164, v165
	v_cvt_pk_bf16_f32 v165, v166, v167
	v_cvt_pk_bf16_f32 v166, v170, v171
	v_cvt_pk_bf16_f32 v167, v168, v169
	global_store_dwordx4 v[154:155], v[164:167], off nt
	v_pk_mul_f32 v[168:169], v[100:101], v[150:151] op_sel_hi:[1,0]
	v_pk_mul_f32 v[170:171], v[98:99], v[150:151] op_sel_hi:[1,0]
	v_pk_mul_f32 v[166:167], v[104:105], v[150:151] op_sel_hi:[1,0]
	v_pk_mul_f32 v[164:165], v[102:103], v[150:151] op_sel_hi:[1,0]
	s_nop 0
	v_cvt_pk_bf16_f32 v164, v164, v165
	v_cvt_pk_bf16_f32 v165, v166, v167
	v_cvt_pk_bf16_f32 v166, v170, v171
	v_cvt_pk_bf16_f32 v167, v168, v169
	global_store_dwordx4 v[154:155], v[164:167], off offset:256 nt
	v_or_b32_e32 v154, 32, v146
	v_lshl_add_u32 v147, v154, 2, s0
	ds_read_b32 v147, v147
	v_ashrrev_i32_e32 v155, 31, v154
	v_lshlrev_b64 v[154:155], 11, v[154:155]
	v_lshl_add_u64 v[154:155], v[152:153], 0, v[154:155]
	s_waitcnt lgkmcnt(0)
	v_mul_f32_e32 v150, 0x3db8aa3b, v147
	v_pk_mul_f32 v[166:167], v[96:97], v[150:151] op_sel_hi:[1,0]
	v_pk_mul_f32 v[164:165], v[94:95], v[150:151] op_sel_hi:[1,0]
	v_pk_mul_f32 v[168:169], v[92:93], v[150:151] op_sel_hi:[1,0]
	v_pk_mul_f32 v[170:171], v[90:91], v[150:151] op_sel_hi:[1,0]
	v_cvt_pk_bf16_f32 v164, v164, v165
	v_cvt_pk_bf16_f32 v165, v166, v167
	v_cvt_pk_bf16_f32 v166, v170, v171
	v_cvt_pk_bf16_f32 v167, v168, v169
	global_store_dwordx4 v[154:155], v[164:167], off nt
	v_pk_mul_f32 v[168:169], v[84:85], v[150:151] op_sel_hi:[1,0]
	v_pk_mul_f32 v[170:171], v[82:83], v[150:151] op_sel_hi:[1,0]
	v_pk_mul_f32 v[166:167], v[88:89], v[150:151] op_sel_hi:[1,0]
	v_pk_mul_f32 v[164:165], v[86:87], v[150:151] op_sel_hi:[1,0]
	s_nop 0
	v_cvt_pk_bf16_f32 v164, v164, v165
	v_cvt_pk_bf16_f32 v165, v166, v167
	v_cvt_pk_bf16_f32 v166, v170, v171
	v_cvt_pk_bf16_f32 v167, v168, v169
	global_store_dwordx4 v[154:155], v[164:167], off offset:256 nt
	v_or_b32_e32 v154, 48, v146
	v_lshl_add_u32 v147, v154, 2, s0
	ds_read_b32 v147, v147
	v_ashrrev_i32_e32 v155, 31, v154
	v_lshlrev_b64 v[154:155], 11, v[154:155]
	v_lshl_add_u64 v[164:165], v[152:153], 0, v[154:155]
	s_mov_b64 s[0:1], 0x40000
	s_waitcnt lgkmcnt(0)
	v_mul_f32_e32 v150, 0x3db8aa3b, v147
	v_pk_mul_f32 v[154:155], v[80:81], v[150:151] op_sel_hi:[1,0]
	v_pk_mul_f32 v[152:153], v[78:79], v[150:151] op_sel_hi:[1,0]
	v_pk_mul_f32 v[166:167], v[76:77], v[150:151] op_sel_hi:[1,0]
	v_pk_mul_f32 v[168:169], v[74:75], v[150:151] op_sel_hi:[1,0]
	v_cvt_pk_bf16_f32 v152, v152, v153
	v_cvt_pk_bf16_f32 v153, v154, v155
	v_cvt_pk_bf16_f32 v154, v168, v169
	v_cvt_pk_bf16_f32 v155, v166, v167
	global_store_dwordx4 v[164:165], v[152:155], off nt
	v_pk_mul_f32 v[166:167], v[68:69], v[150:151] op_sel_hi:[1,0]
	v_pk_mul_f32 v[168:169], v[66:67], v[150:151] op_sel_hi:[1,0]
	v_pk_mul_f32 v[154:155], v[72:73], v[150:151] op_sel_hi:[1,0]
	v_pk_mul_f32 v[152:153], v[70:71], v[150:151] op_sel_hi:[1,0]
	s_nop 0
	v_cvt_pk_bf16_f32 v152, v152, v153
	v_cvt_pk_bf16_f32 v153, v154, v155
	v_cvt_pk_bf16_f32 v154, v168, v169
	v_cvt_pk_bf16_f32 v155, v166, v167
	global_store_dwordx4 v[164:165], v[152:155], off offset:256 nt
	v_lshl_add_u64 v[164:165], v[148:149], 0, s[0:1]
	s_mov_b32 s0, 0x40000
	v_mul_f32_e32 v154, 0x3db8aa3b, v151
	v_pk_mul_f32 v[152:153], v[64:65], v[154:155] op_sel_hi:[1,0]
	v_pk_mul_f32 v[150:151], v[62:63], v[154:155] op_sel_hi:[1,0]
	v_pk_mul_f32 v[166:167], v[60:61], v[154:155] op_sel_hi:[1,0]
	v_pk_mul_f32 v[168:169], v[58:59], v[154:155] op_sel_hi:[1,0]
	v_cvt_pk_bf16_f32 v150, v150, v151
	v_cvt_pk_bf16_f32 v151, v152, v153
	v_cvt_pk_bf16_f32 v153, v166, v167
	v_add_co_u32_e32 v166, vcc, s0, v148
	v_cvt_pk_bf16_f32 v152, v168, v169
	s_nop 0
	v_addc_co_u32_e32 v167, vcc, 0, v149, vcc
	global_store_dwordx4 v[166:167], v[150:153], off nt
	v_pk_mul_f32 v[166:167], v[52:53], v[154:155] op_sel_hi:[1,0]
	s_mov_b64 s[0:1], 0x48000
	v_pk_mul_f32 v[152:153], v[56:57], v[154:155] op_sel_hi:[1,0]
	v_pk_mul_f32 v[150:151], v[54:55], v[154:155] op_sel_hi:[1,0]
	v_pk_mul_f32 v[154:155], v[50:51], v[154:155] op_sel_hi:[1,0]
	v_cvt_pk_bf16_f32 v150, v150, v151
	v_cvt_pk_bf16_f32 v151, v152, v153
	v_cvt_pk_bf16_f32 v152, v154, v155
	ds_read2_b32 v[154:155], v140 offset0:144 offset1:160
	v_cvt_pk_bf16_f32 v153, v166, v167
	global_store_dwordx4 v[164:165], v[150:153], off offset:256 nt
	v_lshl_add_u64 v[164:165], v[148:149], 0, s[0:1]
	s_mov_b32 s0, 0x48000
	s_waitcnt lgkmcnt(0)
	v_mul_f32_e32 v154, 0x3db8aa3b, v154
	v_pk_mul_f32 v[152:153], v[48:49], v[154:155] op_sel_hi:[1,0]
	v_pk_mul_f32 v[150:151], v[46:47], v[154:155] op_sel_hi:[1,0]
	v_pk_mul_f32 v[166:167], v[44:45], v[154:155] op_sel_hi:[1,0]
	v_pk_mul_f32 v[168:169], v[42:43], v[154:155] op_sel_hi:[1,0]
	v_cvt_pk_bf16_f32 v150, v150, v151
	v_cvt_pk_bf16_f32 v151, v152, v153
	v_cvt_pk_bf16_f32 v153, v166, v167
	v_add_co_u32_e32 v166, vcc, s0, v148
	v_cvt_pk_bf16_f32 v152, v168, v169
	s_nop 0
	v_addc_co_u32_e32 v167, vcc, 0, v149, vcc
	global_store_dwordx4 v[166:167], v[150:153], off nt
	v_pk_mul_f32 v[166:167], v[36:37], v[154:155] op_sel_hi:[1,0]
	v_pk_mul_f32 v[168:169], v[34:35], v[154:155] op_sel_hi:[1,0]
	v_pk_mul_f32 v[152:153], v[40:41], v[154:155] op_sel_hi:[1,0]
	v_pk_mul_f32 v[150:151], v[38:39], v[154:155] op_sel_hi:[1,0]
	v_mul_f32_e32 v154, 0x3db8aa3b, v155
	v_cvt_pk_bf16_f32 v150, v150, v151
	v_cvt_pk_bf16_f32 v151, v152, v153
	v_cvt_pk_bf16_f32 v152, v168, v169
	v_cvt_pk_bf16_f32 v153, v166, v167
	s_mov_b64 s[0:1], 0x50000
	ds_read_b32 v140, v140 offset:704
	global_store_dwordx4 v[164:165], v[150:153], off offset:256 nt
	v_lshl_add_u64 v[164:165], v[148:149], 0, s[0:1]
	v_pk_mul_f32 v[166:167], v[28:29], v[154:155] op_sel_hi:[1,0]
	v_pk_mul_f32 v[152:153], v[32:33], v[154:155] op_sel_hi:[1,0]
	v_pk_mul_f32 v[150:151], v[30:31], v[154:155] op_sel_hi:[1,0]
	s_mov_b32 s0, 0x50000
	v_pk_mul_f32 v[168:169], v[26:27], v[154:155] op_sel_hi:[1,0]
	v_cvt_pk_bf16_f32 v150, v150, v151
	v_cvt_pk_bf16_f32 v151, v152, v153
	v_cvt_pk_bf16_f32 v153, v166, v167
	v_add_co_u32_e32 v166, vcc, s0, v148
	v_cvt_pk_bf16_f32 v152, v168, v169
	s_nop 0
	v_addc_co_u32_e32 v167, vcc, 0, v149, vcc
	global_store_dwordx4 v[166:167], v[150:153], off nt
	v_pk_mul_f32 v[166:167], v[20:21], v[154:155] op_sel_hi:[1,0]
	s_mov_b64 s[0:1], 0x58000
	v_pk_mul_f32 v[152:153], v[24:25], v[154:155] op_sel_hi:[1,0]
	v_pk_mul_f32 v[150:151], v[22:23], v[154:155] op_sel_hi:[1,0]
	v_pk_mul_f32 v[154:155], v[18:19], v[154:155] op_sel_hi:[1,0]
	v_cvt_pk_bf16_f32 v150, v150, v151
	v_cvt_pk_bf16_f32 v151, v152, v153
	v_cvt_pk_bf16_f32 v152, v154, v155
	v_cvt_pk_bf16_f32 v153, v166, v167
	s_waitcnt lgkmcnt(0)
	v_mul_f32_e32 v140, 0x3db8aa3b, v140
	v_lshl_add_u64 v[154:155], v[148:149], 0, s[0:1]
	s_mov_b32 s0, 0x58000
	global_store_dwordx4 v[164:165], v[150:153], off offset:256 nt
	v_pk_mul_f32 v[164:165], v[12:13], v[140:141] op_sel_hi:[1,0]
	v_pk_mul_f32 v[166:167], v[10:11], v[140:141] op_sel_hi:[1,0]
	v_pk_mul_f32 v[152:153], v[16:17], v[140:141] op_sel_hi:[1,0]
	v_pk_mul_f32 v[150:151], v[14:15], v[140:141] op_sel_hi:[1,0]
	v_add_co_u32_e32 v148, vcc, s0, v148
	v_cvt_pk_bf16_f32 v150, v150, v151
	v_cvt_pk_bf16_f32 v151, v152, v153
	v_cvt_pk_bf16_f32 v152, v166, v167
	v_cvt_pk_bf16_f32 v153, v164, v165
	v_addc_co_u32_e32 v149, vcc, 0, v149, vcc
	global_store_dwordx4 v[148:149], v[150:153], off nt
	v_pk_mul_f32 v[148:149], v[6:7], v[140:141] op_sel_hi:[1,0]
	v_pk_mul_f32 v[164:165], v[2:3], v[140:141] op_sel_hi:[1,0]
	v_pk_mul_f32 v[150:151], v[8:9], v[140:141] op_sel_hi:[1,0]
	v_pk_mul_f32 v[152:153], v[4:5], v[140:141] op_sel_hi:[1,0]
	v_cvt_pk_bf16_f32 v148, v148, v149
	v_cvt_pk_bf16_f32 v149, v150, v151
	v_cvt_pk_bf16_f32 v150, v164, v165
	v_cvt_pk_bf16_f32 v151, v152, v153
	global_store_dwordx4 v[154:155], v[148:151], off offset:256 nt

.LBB0_659:
	s_andn2_b64 vcc, exec, s[0:1]
	s_cbranch_vccnz .LBB0_661
	s_lshl_b32 s0, s5, 2
	s_add_i32 s0, s0, 0
	v_lshl_add_u32 v140, s6, 8, v160
	s_add_i32 s0, s0, 0x20000
	v_lshl_add_u64 v[148:149], v[140:141], 1, s[42:43]
	v_lshl_add_u32 v140, v146, 2, s0
	ds_read2st64_b32 v[150:151], v140 offset1:2
	v_mad_i64_i32 v[164:165], s[8:9], v146, s89, v[148:149]
	v_or_b32_e32 v147, 16, v146
	s_waitcnt lgkmcnt(0)
	v_pk_mul_f32 v[154:155], v[128:129], v[150:151] op_sel_hi:[1,0]
	v_pk_mul_f32 v[152:153], v[126:127], v[150:151] op_sel_hi:[1,0]
	v_pk_mul_f32 v[166:167], v[124:125], v[150:151] op_sel_hi:[1,0]
	v_pk_mul_f32 v[168:169], v[122:123], v[150:151] op_sel_hi:[1,0]
	v_cvt_pk_bf16_f32 v152, v152, v153
	v_cvt_pk_bf16_f32 v153, v154, v155
	v_cvt_pk_bf16_f32 v154, v168, v169
	v_cvt_pk_bf16_f32 v155, v166, v167
	global_store_dwordx4 v[164:165], v[152:155], off nt
	v_pk_mul_f32 v[166:167], v[116:117], v[150:151] op_sel_hi:[1,0]
	v_pk_mul_f32 v[168:169], v[114:115], v[150:151] op_sel_hi:[1,0]
	v_pk_mul_f32 v[154:155], v[120:121], v[150:151] op_sel_hi:[1,0]
	v_pk_mul_f32 v[152:153], v[118:119], v[150:151] op_sel_hi:[1,0]
	v_lshl_add_u32 v150, v147, 2, s0
	ds_read_b32 v150, v150
	v_cvt_pk_bf16_f32 v152, v152, v153
	v_cvt_pk_bf16_f32 v153, v154, v155
	v_cvt_pk_bf16_f32 v154, v168, v169
	v_cvt_pk_bf16_f32 v155, v166, v167
	global_store_dwordx4 v[164:165], v[152:155], off offset:256 nt
	s_waitcnt lgkmcnt(0)
	v_pk_mul_f32 v[166:167], v[108:109], v[150:151] op_sel_hi:[1,0]
	v_pk_mul_f32 v[168:169], v[106:107], v[150:151] op_sel_hi:[1,0]
	v_pk_mul_f32 v[154:155], v[112:113], v[150:151] op_sel_hi:[1,0]
	v_pk_mul_f32 v[152:153], v[110:111], v[150:151] op_sel_hi:[1,0]
	v_mad_i64_i32 v[164:165], s[8:9], v147, s89, v[148:149]
	v_cvt_pk_bf16_f32 v152, v152, v153
	v_cvt_pk_bf16_f32 v153, v154, v155
	v_cvt_pk_bf16_f32 v154, v168, v169
	v_cvt_pk_bf16_f32 v155, v166, v167
	v_or_b32_e32 v147, 32, v146
	global_store_dwordx4 v[164:165], v[152:155], off nt
	v_pk_mul_f32 v[166:167], v[100:101], v[150:151] op_sel_hi:[1,0]
	v_pk_mul_f32 v[168:169], v[98:99], v[150:151] op_sel_hi:[1,0]
	v_pk_mul_f32 v[154:155], v[104:105], v[150:151] op_sel_hi:[1,0]
	v_pk_mul_f32 v[152:153], v[102:103], v[150:151] op_sel_hi:[1,0]
	v_lshl_add_u32 v150, v147, 2, s0
	ds_read_b32 v150, v150
	v_cvt_pk_bf16_f32 v152, v152, v153
	v_cvt_pk_bf16_f32 v153, v154, v155
	v_cvt_pk_bf16_f32 v154, v168, v169
	v_cvt_pk_bf16_f32 v155, v166, v167
	global_store_dwordx4 v[164:165], v[152:155], off offset:256 nt
	s_waitcnt lgkmcnt(0)
	v_pk_mul_f32 v[166:167], v[92:93], v[150:151] op_sel_hi:[1,0]
	v_pk_mul_f32 v[168:169], v[90:91], v[150:151] op_sel_hi:[1,0]
	v_pk_mul_f32 v[154:155], v[96:97], v[150:151] op_sel_hi:[1,0]
	v_pk_mul_f32 v[152:153], v[94:95], v[150:151] op_sel_hi:[1,0]
	v_mad_i64_i32 v[164:165], s[8:9], v147, s89, v[148:149]
	v_cvt_pk_bf16_f32 v152, v152, v153
	v_cvt_pk_bf16_f32 v153, v154, v155
	v_cvt_pk_bf16_f32 v154, v168, v169
	v_cvt_pk_bf16_f32 v155, v166, v167
	v_or_b32_e32 v147, 48, v146
	global_store_dwordx4 v[164:165], v[152:155], off nt
	v_pk_mul_f32 v[166:167], v[84:85], v[150:151] op_sel_hi:[1,0]
	v_pk_mul_f32 v[168:169], v[82:83], v[150:151] op_sel_hi:[1,0]
	v_pk_mul_f32 v[154:155], v[88:89], v[150:151] op_sel_hi:[1,0]
	v_pk_mul_f32 v[152:153], v[86:87], v[150:151] op_sel_hi:[1,0]
	v_lshl_add_u32 v150, v147, 2, s0
	ds_read_b32 v150, v150
	v_cvt_pk_bf16_f32 v152, v152, v153
	v_cvt_pk_bf16_f32 v153, v154, v155
	v_cvt_pk_bf16_f32 v154, v168, v169
	v_cvt_pk_bf16_f32 v155, v166, v167
	global_store_dwordx4 v[164:165], v[152:155], off offset:256 nt
	s_waitcnt lgkmcnt(0)
	v_pk_mul_f32 v[166:167], v[76:77], v[150:151] op_sel_hi:[1,0]
	v_pk_mul_f32 v[168:169], v[74:75], v[150:151] op_sel_hi:[1,0]
	v_pk_mul_f32 v[154:155], v[80:81], v[150:151] op_sel_hi:[1,0]
	v_pk_mul_f32 v[152:153], v[78:79], v[150:151] op_sel_hi:[1,0]
	v_mad_i64_i32 v[164:165], s[0:1], v147, s89, v[148:149]
	v_cvt_pk_bf16_f32 v152, v152, v153
	v_cvt_pk_bf16_f32 v153, v154, v155
	v_cvt_pk_bf16_f32 v154, v168, v169
	v_cvt_pk_bf16_f32 v155, v166, v167
	global_store_dwordx4 v[164:165], v[152:155], off nt
	v_pk_mul_f32 v[166:167], v[68:69], v[150:151] op_sel_hi:[1,0]
	v_pk_mul_f32 v[168:169], v[66:67], v[150:151] op_sel_hi:[1,0]
	v_pk_mul_f32 v[154:155], v[72:73], v[150:151] op_sel_hi:[1,0]
	v_pk_mul_f32 v[152:153], v[70:71], v[150:151] op_sel_hi:[1,0]
	v_add_u32_e32 v147, 0x80, v146
	v_cvt_pk_bf16_f32 v152, v152, v153
	v_cvt_pk_bf16_f32 v153, v154, v155
	v_cvt_pk_bf16_f32 v154, v168, v169
	v_cvt_pk_bf16_f32 v155, v166, v167
	global_store_dwordx4 v[164:165], v[152:155], off offset:256 nt
	v_mov_b32_e32 v164, v151
	v_pk_mul_f32 v[150:151], v[62:63], v[164:165] op_sel_hi:[1,0]
	v_pk_mul_f32 v[152:153], v[64:65], v[164:165] op_sel_hi:[1,0]
	v_pk_mul_f32 v[166:167], v[60:61], v[164:165] op_sel_hi:[1,0]
	v_pk_mul_f32 v[168:169], v[58:59], v[164:165] op_sel_hi:[1,0]
	v_mad_i64_i32 v[154:155], s[0:1], v147, s89, v[148:149]
	v_cvt_pk_bf16_f32 v150, v150, v151
	v_cvt_pk_bf16_f32 v151, v152, v153
	v_cvt_pk_bf16_f32 v152, v168, v169
	v_cvt_pk_bf16_f32 v153, v166, v167
	global_store_dwordx4 v[154:155], v[150:153], off nt
	v_pk_mul_f32 v[166:167], v[52:53], v[164:165] op_sel_hi:[1,0]
	v_add_u32_e32 v147, 0x90, v146
	v_pk_mul_f32 v[152:153], v[56:57], v[164:165] op_sel_hi:[1,0]
	v_pk_mul_f32 v[150:151], v[54:55], v[164:165] op_sel_hi:[1,0]
	v_pk_mul_f32 v[164:165], v[50:51], v[164:165] op_sel_hi:[1,0]
	v_cvt_pk_bf16_f32 v150, v150, v151
	v_cvt_pk_bf16_f32 v151, v152, v153
	v_cvt_pk_bf16_f32 v152, v164, v165
	v_cvt_pk_bf16_f32 v153, v166, v167
	global_store_dwordx4 v[154:155], v[150:153], off offset:256 nt
	ds_read2_b32 v[154:155], v140 offset0:144 offset1:160
	v_mad_i64_i32 v[164:165], s[0:1], v147, s89, v[148:149]
	ds_read_b32 v140, v140 offset:704
	v_add_u32_e32 v147, 0xa0, v146
	s_waitcnt lgkmcnt(0)
	v_pk_mul_f32 v[152:153], v[48:49], v[154:155] op_sel_hi:[1,0]
	v_pk_mul_f32 v[150:151], v[46:47], v[154:155] op_sel_hi:[1,0]
	v_pk_mul_f32 v[166:167], v[44:45], v[154:155] op_sel_hi:[1,0]
	v_pk_mul_f32 v[168:169], v[42:43], v[154:155] op_sel_hi:[1,0]
	v_cvt_pk_bf16_f32 v150, v150, v151
	v_cvt_pk_bf16_f32 v151, v152, v153
	v_cvt_pk_bf16_f32 v152, v168, v169
	v_cvt_pk_bf16_f32 v153, v166, v167
	global_store_dwordx4 v[164:165], v[150:153], off nt
	v_pk_mul_f32 v[166:167], v[36:37], v[154:155] op_sel_hi:[1,0]
	v_pk_mul_f32 v[168:169], v[34:35], v[154:155] op_sel_hi:[1,0]
	v_pk_mul_f32 v[152:153], v[40:41], v[154:155] op_sel_hi:[1,0]
	v_pk_mul_f32 v[150:151], v[38:39], v[154:155] op_sel_hi:[1,0]
	v_mov_b32_e32 v154, v155
	v_cvt_pk_bf16_f32 v150, v150, v151
	v_cvt_pk_bf16_f32 v151, v152, v153
	v_cvt_pk_bf16_f32 v152, v168, v169
	v_cvt_pk_bf16_f32 v153, v166, v167
	global_store_dwordx4 v[164:165], v[150:153], off offset:256 nt
	v_pk_mul_f32 v[166:167], v[28:29], v[154:155] op_sel_hi:[1,0]
	v_pk_mul_f32 v[168:169], v[26:27], v[154:155] op_sel_hi:[1,0]
	v_pk_mul_f32 v[152:153], v[32:33], v[154:155] op_sel_hi:[1,0]
	v_pk_mul_f32 v[150:151], v[30:31], v[154:155] op_sel_hi:[1,0]
	v_mad_i64_i32 v[164:165], s[0:1], v147, s89, v[148:149]
	v_cvt_pk_bf16_f32 v150, v150, v151
	v_cvt_pk_bf16_f32 v151, v152, v153
	v_cvt_pk_bf16_f32 v152, v168, v169
	v_cvt_pk_bf16_f32 v153, v166, v167
	global_store_dwordx4 v[164:165], v[150:153], off nt
	v_pk_mul_f32 v[166:167], v[20:21], v[154:155] op_sel_hi:[1,0]
	v_add_u32_e32 v147, 0xb0, v146
	v_pk_mul_f32 v[152:153], v[24:25], v[154:155] op_sel_hi:[1,0]
	v_pk_mul_f32 v[150:151], v[22:23], v[154:155] op_sel_hi:[1,0]
	v_pk_mul_f32 v[154:155], v[18:19], v[154:155] op_sel_hi:[1,0]
	v_cvt_pk_bf16_f32 v150, v150, v151
	v_cvt_pk_bf16_f32 v151, v152, v153
	v_cvt_pk_bf16_f32 v152, v154, v155
	v_cvt_pk_bf16_f32 v153, v166, v167
	global_store_dwordx4 v[164:165], v[150:153], off offset:256 nt
	v_pk_mul_f32 v[154:155], v[12:13], v[140:141] op_sel_hi:[1,0]
	v_pk_mul_f32 v[164:165], v[10:11], v[140:141] op_sel_hi:[1,0]
	v_mad_i64_i32 v[152:153], s[0:1], v147, s89, v[148:149]
	v_pk_mul_f32 v[150:151], v[16:17], v[140:141] op_sel_hi:[1,0]
	v_pk_mul_f32 v[148:149], v[14:15], v[140:141] op_sel_hi:[1,0]
	s_nop 0
	v_cvt_pk_bf16_f32 v148, v148, v149
	v_cvt_pk_bf16_f32 v149, v150, v151
	v_cvt_pk_bf16_f32 v150, v164, v165
	v_cvt_pk_bf16_f32 v151, v154, v155
	global_store_dwordx4 v[152:153], v[148:151], off nt
	v_pk_mul_f32 v[154:155], v[4:5], v[140:141] op_sel_hi:[1,0]
	v_pk_mul_f32 v[164:165], v[2:3], v[140:141] op_sel_hi:[1,0]
	v_pk_mul_f32 v[150:151], v[8:9], v[140:141] op_sel_hi:[1,0]
	v_pk_mul_f32 v[148:149], v[6:7], v[140:141] op_sel_hi:[1,0]
	s_nop 0
	v_cvt_pk_bf16_f32 v148, v148, v149
	v_cvt_pk_bf16_f32 v149, v150, v151
	v_cvt_pk_bf16_f32 v150, v164, v165
	v_cvt_pk_bf16_f32 v151, v154, v155
	global_store_dwordx4 v[152:153], v[148:151], off offset:256 nt

.LBB0_664:
	s_lshl_b32 s0, s5, 2
	s_add_i32 s26, s0, 0
	v_lshl_add_u32 v140, v146, 2, s26
	v_add_u32_e32 v140, 0x20000, v140
	ds_read_b32 v150, v140
	s_ashr_i32 s12, s4, 11
	s_mul_hi_i32 s11, s12, 0x6700
	s_mulk_i32 s12, 0x6700
	v_cmp_lt_i32_e32 vcc, s91, v146
	v_cmp_gt_i32_e64 s[4:5], s95, v146
	s_and_saveexec_b64 s[0:1], s[4:5]
	s_xor_b64 s[0:1], exec, s[0:1]
	s_add_u32 s8, s24, s12
	s_addc_u32 s9, s25, s11
	s_or_saveexec_b64 s[0:1], s[0:1]
	v_mov_b64_e32 v[152:153], s[8:9]
	s_xor_b64 exec, exec, s[0:1]
	v_add_u32_e32 v147, 0xffffe000, v146
	v_lshrrev_b32_e32 v147, 2, v147
	v_mov_b64_e32 v[148:149], s[30:31]
	v_mad_u64_u32 v[152:153], s[4:5], v147, s90, v[148:149]
	s_or_b64 exec, exec, s[0:1]
	v_mov_b64_e32 v[154:155], s[16:17]
	v_lshl_or_b32 v148, s6, 8, v157
	v_mad_i64_i32 v[154:155], s[0:1], v146, s18, v[154:155]
	v_ashrrev_i32_e32 v149, 31, v148
	s_and_b64 s[0:1], s[2:3], vcc
	s_waitcnt lgkmcnt(0)
	v_pk_mul_f32 v[128:129], v[128:129], v[150:151] op_sel_hi:[1,0]
	v_pk_mul_f32 v[126:127], v[126:127], v[150:151] op_sel_hi:[1,0]
	v_pk_mul_f32 v[124:125], v[124:125], v[150:151] op_sel_hi:[1,0]
	v_pk_mul_f32 v[122:123], v[122:123], v[150:151] op_sel_hi:[1,0]
	v_cmp_gt_i32_e32 vcc, s19, v148
	v_lshl_add_u64 v[154:155], v[148:149], 1, v[154:155]
	v_lshl_add_u64 v[152:153], v[148:149], 2, v[152:153]
	v_cvt_pk_bf16_f32 v164, v126, v127
	v_cvt_pk_bf16_f32 v165, v128, v129
	v_cvt_pk_bf16_f32 v166, v122, v123
	v_cvt_pk_bf16_f32 v167, v124, v125
	s_and_b64 s[6:7], s[0:1], vcc
	global_store_dwordx4 v[154:155], v[164:167], off nt
	s_and_saveexec_b64 s[4:5], s[6:7]
	s_cbranch_execz .LBB0_670
	global_store_dwordx4 v[152:153], v[126:129], off nt
	global_store_dwordx4 v[152:153], v[122:125], off offset:16 nt
.LBB0_670:
	s_or_b64 exec, exec, s[4:5]
	v_mov_b32_e32 v151, v150
	v_mov_b32_e32 v122, v150
	v_mov_b32_e32 v123, v150
	v_pk_mul_f32 v[120:121], v[120:121], v[122:123]
	v_pk_mul_f32 v[118:119], v[118:119], v[150:151]
	v_pk_mul_f32 v[116:117], v[116:117], v[122:123]
	v_pk_mul_f32 v[114:115], v[114:115], v[150:151]
	v_cvt_pk_bf16_f32 v122, v118, v119
	v_cvt_pk_bf16_f32 v123, v120, v121
	v_cvt_pk_bf16_f32 v124, v114, v115
	v_cvt_pk_bf16_f32 v125, v116, v117
	global_store_dwordx4 v[154:155], v[122:125], off offset:256 nt
	s_nop 1
	v_or_b32_e32 v122, 0x80, v148
	v_cmp_gt_i32_e64 s[4:5], s19, v122
	s_and_b64 s[6:7], s[0:1], s[4:5]
	s_and_saveexec_b64 s[0:1], s[6:7]
	s_cbranch_execz .LBB0_672
	global_store_dwordx4 v[152:153], v[118:121], off offset:512 nt
	global_store_dwordx4 v[152:153], v[114:117], off offset:528 nt
.LBB0_672:
	s_or_b64 exec, exec, s[0:1]
	s_nop 0
	v_or_b32_e32 v115, 16, v146
	s_add_i32 s26, s26, 0x20000
	v_lshl_add_u32 v114, v115, 2, s26
	ds_read_b32 v114, v114
	v_cmp_lt_i32_e64 s[6:7], s91, v115
	v_cmp_gt_i32_e64 s[8:9], s95, v115
	s_and_saveexec_b64 s[0:1], s[8:9]
	s_xor_b64 s[0:1], exec, s[0:1]
	s_add_u32 s52, s24, s12
	s_addc_u32 s53, s25, s11
	s_or_saveexec_b64 s[0:1], s[0:1]
	v_mov_b64_e32 v[116:117], s[52:53]
	s_xor_b64 exec, exec, s[0:1]
	v_add_u32_e32 v116, 0xffffe010, v146
	v_lshrrev_b32_e32 v118, 2, v116
	v_mov_b64_e32 v[116:117], s[30:31]
	v_mad_u64_u32 v[116:117], s[8:9], v118, s90, v[116:117]
	s_or_b64 exec, exec, s[0:1]
	v_mov_b64_e32 v[118:119], s[16:17]
	v_mad_i64_i32 v[118:119], s[0:1], v115, s18, v[118:119]
	s_and_b64 s[0:1], s[2:3], s[6:7]
	s_waitcnt lgkmcnt(0)
	v_pk_mul_f32 v[112:113], v[112:113], v[114:115] op_sel_hi:[1,0]
	v_pk_mul_f32 v[110:111], v[110:111], v[114:115] op_sel_hi:[1,0]
	v_pk_mul_f32 v[108:109], v[108:109], v[114:115] op_sel_hi:[1,0]
	v_pk_mul_f32 v[106:107], v[106:107], v[114:115] op_sel_hi:[1,0]
	v_lshl_add_u64 v[118:119], v[148:149], 1, v[118:119]
	v_lshl_add_u64 v[116:117], v[148:149], 2, v[116:117]
	v_cvt_pk_bf16_f32 v120, v110, v111
	v_cvt_pk_bf16_f32 v121, v112, v113
	v_cvt_pk_bf16_f32 v122, v106, v107
	v_cvt_pk_bf16_f32 v123, v108, v109
	s_and_b64 s[8:9], s[0:1], vcc
	global_store_dwordx4 v[118:119], v[120:123], off nt
	s_and_saveexec_b64 s[6:7], s[8:9]
	s_cbranch_execz .LBB0_678
	global_store_dwordx4 v[116:117], v[110:113], off nt
	global_store_dwordx4 v[116:117], v[106:109], off offset:16 nt
.LBB0_678:
	s_or_b64 exec, exec, s[6:7]
	v_mov_b32_e32 v115, v114
	v_mov_b32_e32 v106, v114
	v_mov_b32_e32 v107, v114
	v_pk_mul_f32 v[104:105], v[104:105], v[106:107]
	v_pk_mul_f32 v[102:103], v[102:103], v[114:115]
	v_pk_mul_f32 v[100:101], v[100:101], v[106:107]
	v_pk_mul_f32 v[98:99], v[98:99], v[114:115]
	v_cvt_pk_bf16_f32 v106, v102, v103
	v_cvt_pk_bf16_f32 v107, v104, v105
	v_cvt_pk_bf16_f32 v108, v98, v99
	v_cvt_pk_bf16_f32 v109, v100, v101
	s_and_b64 s[6:7], s[0:1], s[4:5]
	global_store_dwordx4 v[118:119], v[106:109], off offset:256 nt
	s_and_saveexec_b64 s[0:1], s[6:7]
	s_cbranch_execz .LBB0_680
	global_store_dwordx4 v[116:117], v[102:105], off offset:512 nt
	global_store_dwordx4 v[116:117], v[98:101], off offset:528 nt
.LBB0_680:
	s_or_b64 exec, exec, s[0:1]
	s_nop 0
	v_or_b32_e32 v99, 32, v146
	v_lshl_add_u32 v98, v99, 2, s26
	ds_read_b32 v98, v98
	v_cmp_lt_i32_e64 s[6:7], s91, v99
	v_cmp_gt_i32_e64 s[8:9], s95, v99
	s_and_saveexec_b64 s[0:1], s[8:9]
	s_xor_b64 s[0:1], exec, s[0:1]
	s_add_u32 s52, s24, s12
	s_addc_u32 s53, s25, s11
	s_or_saveexec_b64 s[0:1], s[0:1]
	v_mov_b64_e32 v[100:101], s[52:53]
	s_xor_b64 exec, exec, s[0:1]
	v_add_u32_e32 v100, 0xffffe020, v146
	v_lshrrev_b32_e32 v102, 2, v100
	v_mov_b64_e32 v[100:101], s[30:31]
	v_mad_u64_u32 v[100:101], s[8:9], v102, s90, v[100:101]
	s_or_b64 exec, exec, s[0:1]
	v_mov_b64_e32 v[102:103], s[16:17]
	v_mad_i64_i32 v[102:103], s[0:1], v99, s18, v[102:103]
	s_and_b64 s[0:1], s[2:3], s[6:7]
	s_waitcnt lgkmcnt(0)
	v_pk_mul_f32 v[96:97], v[96:97], v[98:99] op_sel_hi:[1,0]
	v_pk_mul_f32 v[94:95], v[94:95], v[98:99] op_sel_hi:[1,0]
	v_pk_mul_f32 v[92:93], v[92:93], v[98:99] op_sel_hi:[1,0]
	v_pk_mul_f32 v[90:91], v[90:91], v[98:99] op_sel_hi:[1,0]
	v_lshl_add_u64 v[102:103], v[148:149], 1, v[102:103]
	v_lshl_add_u64 v[100:101], v[148:149], 2, v[100:101]
	v_cvt_pk_bf16_f32 v104, v94, v95
	v_cvt_pk_bf16_f32 v105, v96, v97
	v_cvt_pk_bf16_f32 v106, v90, v91
	v_cvt_pk_bf16_f32 v107, v92, v93
	s_and_b64 s[8:9], s[0:1], vcc
	global_store_dwordx4 v[102:103], v[104:107], off nt
	s_and_saveexec_b64 s[6:7], s[8:9]
	s_cbranch_execz .LBB0_686
	global_store_dwordx4 v[100:101], v[94:97], off nt
	global_store_dwordx4 v[100:101], v[90:93], off offset:16 nt
.LBB0_686:
	s_or_b64 exec, exec, s[6:7]
	v_mov_b32_e32 v99, v98
	v_mov_b32_e32 v90, v98
	v_mov_b32_e32 v91, v98
	v_pk_mul_f32 v[88:89], v[88:89], v[90:91]
	v_pk_mul_f32 v[86:87], v[86:87], v[98:99]
	v_pk_mul_f32 v[84:85], v[84:85], v[90:91]
	v_pk_mul_f32 v[82:83], v[82:83], v[98:99]
	v_cvt_pk_bf16_f32 v90, v86, v87
	v_cvt_pk_bf16_f32 v91, v88, v89
	v_cvt_pk_bf16_f32 v92, v82, v83
	v_cvt_pk_bf16_f32 v93, v84, v85
	s_and_b64 s[6:7], s[0:1], s[4:5]
	global_store_dwordx4 v[102:103], v[90:93], off offset:256 nt
	s_and_saveexec_b64 s[0:1], s[6:7]
	s_cbranch_execz .LBB0_688
	global_store_dwordx4 v[100:101], v[86:89], off offset:512 nt
	global_store_dwordx4 v[100:101], v[82:85], off offset:528 nt
.LBB0_688:
	s_or_b64 exec, exec, s[0:1]
	s_nop 0
	v_or_b32_e32 v83, 48, v146
	v_lshl_add_u32 v82, v83, 2, s26
	ds_read_b32 v82, v82
	v_cmp_gt_i32_e64 s[6:7], s95, v83
	v_cmp_lt_i32_e64 s[8:9], s91, v83
	s_and_saveexec_b64 s[0:1], s[8:9]
	s_xor_b64 s[0:1], exec, s[0:1]
	v_add_u32_e32 v84, 0xffffe030, v146
	v_lshrrev_b32_e32 v86, 2, v84
	v_mov_b64_e32 v[84:85], s[30:31]
	v_mad_u64_u32 v[84:85], s[8:9], v86, s90, v[84:85]
	s_andn2_saveexec_b64 s[0:1], s[0:1]
	s_add_u32 s8, s24, s12
	s_addc_u32 s9, s25, s11
	v_mov_b64_e32 v[84:85], s[8:9]
	s_or_b64 exec, exec, s[0:1]
	v_mov_b64_e32 v[86:87], s[16:17]
	v_mad_i64_i32 v[86:87], s[0:1], v83, s18, v[86:87]
	v_and_b32_e32 v83, 0x7ff, v83
	v_cmp_eq_u32_e64 s[8:9], s10, v83
	v_cndmask_b32_e64 v88, 0, 1, s[2:3]
	v_lshl_add_u64 v[86:87], v[148:149], 1, v[86:87]
	v_cndmask_b32_e64 v83, 0, 1, s[8:9]
	v_cndmask_b32_e64 v83, v88, v83, s[6:7]
	v_and_b32_e32 v83, 1, v83
	v_cmp_eq_u32_e64 s[6:7], 1, v83
	s_waitcnt lgkmcnt(0)
	v_pk_mul_f32 v[80:81], v[80:81], v[82:83] op_sel_hi:[1,0]
	v_pk_mul_f32 v[78:79], v[78:79], v[82:83] op_sel_hi:[1,0]
	v_pk_mul_f32 v[76:77], v[76:77], v[82:83] op_sel_hi:[1,0]
	v_pk_mul_f32 v[74:75], v[74:75], v[82:83] op_sel_hi:[1,0]
	v_lshl_add_u64 v[84:85], v[148:149], 2, v[84:85]
	v_cvt_pk_bf16_f32 v90, v78, v79
	v_cvt_pk_bf16_f32 v91, v80, v81
	v_cvt_pk_bf16_f32 v92, v74, v75
	v_cvt_pk_bf16_f32 v93, v76, v77
	s_and_b64 s[8:9], s[6:7], vcc
	global_store_dwordx4 v[86:87], v[90:93], off nt
	s_and_saveexec_b64 s[0:1], s[8:9]
	s_cbranch_execz .LBB0_694
	global_store_dwordx4 v[84:85], v[78:81], off nt
	global_store_dwordx4 v[84:85], v[74:77], off offset:16 nt
.LBB0_694:
	s_or_b64 exec, exec, s[0:1]
	v_mov_b32_e32 v83, v82
	v_mov_b32_e32 v74, v82
	v_mov_b32_e32 v75, v82
	v_pk_mul_f32 v[72:73], v[72:73], v[74:75]
	v_pk_mul_f32 v[70:71], v[70:71], v[82:83]
	v_pk_mul_f32 v[68:69], v[68:69], v[74:75]
	v_pk_mul_f32 v[66:67], v[66:67], v[82:83]
	v_cvt_pk_bf16_f32 v74, v70, v71
	v_cvt_pk_bf16_f32 v75, v72, v73
	v_cvt_pk_bf16_f32 v76, v66, v67
	v_cvt_pk_bf16_f32 v77, v68, v69
	s_and_b64 s[6:7], s[6:7], s[4:5]
	global_store_dwordx4 v[86:87], v[74:77], off offset:256 nt
	s_and_saveexec_b64 s[0:1], s[6:7]
	s_cbranch_execz .LBB0_696
	global_store_dwordx4 v[84:85], v[70:73], off offset:512 nt
	global_store_dwordx4 v[84:85], v[66:69], off offset:528 nt
.LBB0_696:
	s_or_b64 exec, exec, s[0:1]
	ds_read_b32 v70, v140 offset:512
	v_add_u32_e32 v71, 0x80, v146
	v_ashrrev_i32_e32 v66, 11, v71
	s_movk_i32 s0, 0x1f7f
	v_mul_hi_i32_i24_e32 v69, 0x6700, v66
	v_mul_i32_i24_e32 v68, 0x6700, v66
	v_cmp_lt_i32_e64 s[6:7], s0, v146
	s_movk_i32 s0, 0x1f80
	v_cmp_gt_i32_e64 s[8:9], s0, v146
	v_lshl_add_u64 v[66:67], s[24:25], 0, v[68:69]
	s_and_saveexec_b64 s[0:1], s[8:9]
	s_xor_b64 s[0:1], exec, s[0:1]
	v_lshl_add_u64 v[72:73], s[24:25], 0, v[68:69]
	s_andn2_saveexec_b64 s[0:1], s[0:1]
	v_add_u32_e32 v72, 0xffffe080, v146
	v_lshrrev_b32_e32 v74, 2, v72
	v_mov_b64_e32 v[72:73], s[30:31]
	v_mad_u64_u32 v[72:73], s[8:9], v74, s90, v[72:73]
	s_or_b64 exec, exec, s[0:1]
	v_mov_b64_e32 v[74:75], s[16:17]
	v_mad_i64_i32 v[74:75], s[0:1], v71, s18, v[74:75]
	s_and_b64 s[0:1], s[2:3], s[6:7]
	s_waitcnt lgkmcnt(0)
	v_pk_mul_f32 v[64:65], v[64:65], v[70:71] op_sel_hi:[1,0]
	v_pk_mul_f32 v[62:63], v[62:63], v[70:71] op_sel_hi:[1,0]
	v_pk_mul_f32 v[60:61], v[60:61], v[70:71] op_sel_hi:[1,0]
	v_pk_mul_f32 v[58:59], v[58:59], v[70:71] op_sel_hi:[1,0]
	v_lshl_add_u64 v[74:75], v[148:149], 1, v[74:75]
	v_lshl_add_u64 v[72:73], v[148:149], 2, v[72:73]
	v_cvt_pk_bf16_f32 v76, v62, v63
	v_cvt_pk_bf16_f32 v77, v64, v65
	v_cvt_pk_bf16_f32 v78, v58, v59
	v_cvt_pk_bf16_f32 v79, v60, v61
	s_and_b64 s[8:9], s[0:1], vcc
	global_store_dwordx4 v[74:75], v[76:79], off nt
	s_and_saveexec_b64 s[6:7], s[8:9]
	s_cbranch_execz .LBB0_702
	global_store_dwordx4 v[72:73], v[62:65], off nt
	global_store_dwordx4 v[72:73], v[58:61], off offset:16 nt
.LBB0_702:
	s_or_b64 exec, exec, s[6:7]
	v_mov_b32_e32 v71, v70
	v_mov_b32_e32 v58, v70
	v_mov_b32_e32 v59, v70
	v_pk_mul_f32 v[56:57], v[56:57], v[58:59]
	v_pk_mul_f32 v[54:55], v[54:55], v[70:71]
	v_pk_mul_f32 v[52:53], v[52:53], v[58:59]
	v_pk_mul_f32 v[50:51], v[50:51], v[70:71]
	v_cvt_pk_bf16_f32 v58, v54, v55
	v_cvt_pk_bf16_f32 v59, v56, v57
	v_cvt_pk_bf16_f32 v60, v50, v51
	v_cvt_pk_bf16_f32 v61, v52, v53
	s_and_b64 s[6:7], s[0:1], s[4:5]
	global_store_dwordx4 v[74:75], v[58:61], off offset:256 nt
	s_and_saveexec_b64 s[0:1], s[6:7]
	s_cbranch_execz .LBB0_704
	global_store_dwordx4 v[72:73], v[54:57], off offset:512 nt
	global_store_dwordx4 v[72:73], v[50:53], off offset:528 nt
.LBB0_704:
	s_or_b64 exec, exec, s[0:1]
	ds_read_b32 v50, v140 offset:576
	s_movk_i32 s0, 0x1f6f
	v_cmp_lt_i32_e64 s[6:7], s0, v146
	s_movk_i32 s0, 0x1f70
	v_cmp_gt_i32_e64 s[8:9], s0, v146
	s_and_saveexec_b64 s[0:1], s[8:9]
	s_xor_b64 s[0:1], exec, s[0:1]
	v_lshl_add_u64 v[52:53], s[24:25], 0, v[68:69]
	s_andn2_saveexec_b64 s[0:1], s[0:1]
	v_add_u32_e32 v51, 0xffffe090, v146
	v_lshrrev_b32_e32 v51, 2, v51
	v_mov_b64_e32 v[52:53], s[30:31]
	v_mad_u64_u32 v[52:53], s[8:9], v51, s90, v[52:53]
	s_or_b64 exec, exec, s[0:1]
	v_add_u32_e32 v51, 0x90, v146
	v_mov_b64_e32 v[54:55], s[16:17]
	v_mad_i64_i32 v[54:55], s[0:1], v51, s18, v[54:55]
	s_and_b64 s[0:1], s[2:3], s[6:7]
	s_waitcnt lgkmcnt(0)
	v_pk_mul_f32 v[48:49], v[48:49], v[50:51] op_sel_hi:[1,0]
	v_pk_mul_f32 v[46:47], v[46:47], v[50:51] op_sel_hi:[1,0]
	v_pk_mul_f32 v[44:45], v[44:45], v[50:51] op_sel_hi:[1,0]
	v_pk_mul_f32 v[42:43], v[42:43], v[50:51] op_sel_hi:[1,0]
	v_lshl_add_u64 v[54:55], v[148:149], 1, v[54:55]
	v_lshl_add_u64 v[52:53], v[148:149], 2, v[52:53]
	v_cvt_pk_bf16_f32 v56, v46, v47
	v_cvt_pk_bf16_f32 v57, v48, v49
	v_cvt_pk_bf16_f32 v58, v42, v43
	v_cvt_pk_bf16_f32 v59, v44, v45
	s_and_b64 s[8:9], s[0:1], vcc
	global_store_dwordx4 v[54:55], v[56:59], off nt
	s_and_saveexec_b64 s[6:7], s[8:9]
	s_cbranch_execz .LBB0_710
	global_store_dwordx4 v[52:53], v[46:49], off nt
	global_store_dwordx4 v[52:53], v[42:45], off offset:16 nt
.LBB0_710:
	s_or_b64 exec, exec, s[6:7]
	v_mov_b32_e32 v51, v50
	v_mov_b32_e32 v42, v50
	v_mov_b32_e32 v43, v50
	v_pk_mul_f32 v[40:41], v[40:41], v[42:43]
	v_pk_mul_f32 v[38:39], v[38:39], v[50:51]
	v_pk_mul_f32 v[36:37], v[36:37], v[42:43]
	v_pk_mul_f32 v[34:35], v[34:35], v[50:51]
	v_cvt_pk_bf16_f32 v42, v38, v39
	v_cvt_pk_bf16_f32 v43, v40, v41
	v_cvt_pk_bf16_f32 v44, v34, v35
	v_cvt_pk_bf16_f32 v45, v36, v37
	s_and_b64 s[6:7], s[0:1], s[4:5]
	global_store_dwordx4 v[54:55], v[42:45], off offset:256 nt
	s_and_saveexec_b64 s[0:1], s[6:7]
	s_cbranch_execz .LBB0_712
	global_store_dwordx4 v[52:53], v[38:41], off offset:512 nt
	global_store_dwordx4 v[52:53], v[34:37], off offset:528 nt
.LBB0_712:
	s_or_b64 exec, exec, s[0:1]
	ds_read_b32 v34, v140 offset:640
	s_movk_i32 s0, 0x1f5f
	v_cmp_lt_i32_e64 s[6:7], s0, v146
	s_movk_i32 s0, 0x1f60
	v_cmp_gt_i32_e64 s[8:9], s0, v146
	s_and_saveexec_b64 s[0:1], s[8:9]
	s_xor_b64 s[0:1], exec, s[0:1]
	v_lshl_add_u64 v[36:37], s[24:25], 0, v[68:69]
	s_andn2_saveexec_b64 s[0:1], s[0:1]
	v_add_u32_e32 v35, 0xffffe0a0, v146
	v_lshrrev_b32_e32 v35, 2, v35
	v_mov_b64_e32 v[36:37], s[30:31]
	v_mad_u64_u32 v[36:37], s[8:9], v35, s90, v[36:37]
	s_or_b64 exec, exec, s[0:1]
	v_add_u32_e32 v35, 0xa0, v146
	v_mov_b64_e32 v[38:39], s[16:17]
	v_mad_i64_i32 v[38:39], s[0:1], v35, s18, v[38:39]
	s_and_b64 s[0:1], s[2:3], s[6:7]
	s_waitcnt lgkmcnt(0)
	v_pk_mul_f32 v[32:33], v[32:33], v[34:35] op_sel_hi:[1,0]
	v_pk_mul_f32 v[30:31], v[30:31], v[34:35] op_sel_hi:[1,0]
	v_pk_mul_f32 v[28:29], v[28:29], v[34:35] op_sel_hi:[1,0]
	v_pk_mul_f32 v[26:27], v[26:27], v[34:35] op_sel_hi:[1,0]
	v_lshl_add_u64 v[38:39], v[148:149], 1, v[38:39]
	v_lshl_add_u64 v[36:37], v[148:149], 2, v[36:37]
	v_cvt_pk_bf16_f32 v40, v30, v31
	v_cvt_pk_bf16_f32 v41, v32, v33
	v_cvt_pk_bf16_f32 v42, v26, v27
	v_cvt_pk_bf16_f32 v43, v28, v29
	s_and_b64 s[8:9], s[0:1], vcc
	global_store_dwordx4 v[38:39], v[40:43], off nt
	s_and_saveexec_b64 s[6:7], s[8:9]
	s_cbranch_execz .LBB0_718
	global_store_dwordx4 v[36:37], v[30:33], off nt
	global_store_dwordx4 v[36:37], v[26:29], off offset:16 nt
.LBB0_718:
	s_or_b64 exec, exec, s[6:7]
	v_mov_b32_e32 v35, v34
	v_mov_b32_e32 v26, v34
	v_mov_b32_e32 v27, v34
	v_pk_mul_f32 v[24:25], v[24:25], v[26:27]
	v_pk_mul_f32 v[22:23], v[22:23], v[34:35]
	v_pk_mul_f32 v[20:21], v[20:21], v[26:27]
	v_pk_mul_f32 v[18:19], v[18:19], v[34:35]
	v_cvt_pk_bf16_f32 v26, v22, v23
	v_cvt_pk_bf16_f32 v27, v24, v25
	v_cvt_pk_bf16_f32 v28, v18, v19
	v_cvt_pk_bf16_f32 v29, v20, v21
	s_and_b64 s[6:7], s[0:1], s[4:5]
	global_store_dwordx4 v[38:39], v[26:29], off offset:256 nt
	s_and_saveexec_b64 s[0:1], s[6:7]
	s_cbranch_execz .LBB0_720
	global_store_dwordx4 v[36:37], v[22:25], off offset:512 nt
	global_store_dwordx4 v[36:37], v[18:21], off offset:528 nt
.LBB0_720:
	s_or_b64 exec, exec, s[0:1]
	ds_read_b32 v18, v140 offset:704
	s_movk_i32 s0, 0x1f50
	v_cmp_gt_i32_e64 s[6:7], s0, v146
	s_movk_i32 s0, 0x1f4f
	v_cmp_lt_i32_e64 s[8:9], s0, v146
	s_and_saveexec_b64 s[0:1], s[8:9]
	s_xor_b64 s[0:1], exec, s[0:1]
	v_add_u32_e32 v19, 0xffffe0b0, v146
	v_lshrrev_b32_e32 v19, 2, v19
	v_mov_b64_e32 v[20:21], s[30:31]
	v_mad_u64_u32 v[66:67], s[8:9], v19, s90, v[20:21]
	s_andn2_saveexec_b64 s[0:1], s[0:1]
	s_or_b64 exec, exec, s[0:1]
	v_add_u32_e32 v19, 0xb0, v146
	v_mov_b64_e32 v[20:21], s[16:17]
	v_mad_i64_i32 v[20:21], s[0:1], v19, s18, v[20:21]
	v_and_b32_e32 v19, 0x7ff, v19
	v_cmp_eq_u32_e64 s[8:9], s10, v19
	v_lshl_add_u64 v[22:23], v[148:149], 1, v[20:21]
	v_lshl_add_u64 v[20:21], v[148:149], 2, v[66:67]
	v_cndmask_b32_e64 v19, 0, 1, s[8:9]
	v_cndmask_b32_e64 v19, v88, v19, s[6:7]
	v_and_b32_e32 v19, 1, v19
	v_cmp_eq_u32_e64 s[6:7], 1, v19
	s_waitcnt lgkmcnt(0)
	v_pk_mul_f32 v[16:17], v[16:17], v[18:19] op_sel_hi:[1,0]
	v_pk_mul_f32 v[14:15], v[14:15], v[18:19] op_sel_hi:[1,0]
	v_pk_mul_f32 v[12:13], v[12:13], v[18:19] op_sel_hi:[1,0]
	v_pk_mul_f32 v[10:11], v[10:11], v[18:19] op_sel_hi:[1,0]
	v_cvt_pk_bf16_f32 v24, v14, v15
	v_cvt_pk_bf16_f32 v25, v16, v17
	v_cvt_pk_bf16_f32 v26, v10, v11
	v_cvt_pk_bf16_f32 v27, v12, v13
	s_and_b64 s[8:9], s[6:7], vcc
	global_store_dwordx4 v[22:23], v[24:27], off nt
	s_and_saveexec_b64 s[0:1], s[8:9]
	s_cbranch_execz .LBB0_724
	global_store_dwordx4 v[20:21], v[14:17], off nt
	global_store_dwordx4 v[20:21], v[10:13], off offset:16 nt
.LBB0_724:
	s_or_b64 exec, exec, s[0:1]
	v_mov_b32_e32 v19, v18
	v_mov_b32_e32 v10, v18
	v_mov_b32_e32 v11, v18
	v_pk_mul_f32 v[8:9], v[8:9], v[10:11]
	v_pk_mul_f32 v[6:7], v[6:7], v[18:19]
	v_pk_mul_f32 v[4:5], v[4:5], v[10:11]
	v_pk_mul_f32 v[2:3], v[2:3], v[18:19]
	v_cvt_pk_bf16_f32 v10, v6, v7
	v_cvt_pk_bf16_f32 v11, v8, v9
	v_cvt_pk_bf16_f32 v12, v2, v3
	v_cvt_pk_bf16_f32 v13, v4, v5
	s_and_b64 s[4:5], s[6:7], s[4:5]
	global_store_dwordx4 v[22:23], v[10:13], off offset:256 nt
	s_and_saveexec_b64 s[0:1], s[4:5]
	s_cbranch_execz .LBB0_726
	global_store_dwordx4 v[20:21], v[6:9], off offset:512 nt
	global_store_dwordx4 v[20:21], v[2:5], off offset:528 nt

.LBB0_1647:
	s_lshl_b32 s15, s2, 8
	s_add_i32 s17, s15, 0xffffe100
	s_cmp_gt_i32 s2, 31
	s_cselect_b32 s2, s17, 0
	s_sub_i32 s2, s2, s15
	s_lshl_b32 s2, s2, 2
	s_add_i32 s2, s2, 0
	v_add_u32_e32 v152, s15, v146
	s_add_i32 s2, s2, 0x20000
	v_lshl_add_u32 v153, v152, 2, s2
	ds_read2st64_b32 v[144:145], v153 offset1:2
	v_lshl_or_b32 v154, s24, 7, v148
	s_andn2_b64 vcc, exec, s[18:19]
	s_mov_b64 s[18:19], -1
	s_waitcnt lgkmcnt(0)
	v_pk_mul_f32 v[126:127], v[126:127], v[144:145] op_sel_hi:[1,0]
	s_nop 0
	v_mul_f32_e32 v155, 0xbfb8aa3b, v126
	v_mul_f32_e32 v156, 0xbfb8aa3b, v127
	v_exp_f32_e32 v157, v155
	v_exp_f32_e32 v156, v156
	v_pk_mul_f32 v[128:129], v[128:129], v[144:145] op_sel_hi:[1,0]
	v_pk_mul_f32 v[118:119], v[118:119], v[144:145] op_sel_hi:[1,0]
	v_add_f32_e32 v157, 1.0, v157
	v_add_f32_e32 v158, 1.0, v156
	v_rcp_f32_e32 v156, v157
	v_mul_f32_e32 v157, 0xbfb8aa3b, v128
	v_exp_f32_e32 v159, v157
	v_mul_f32_e32 v157, 0xbfb8aa3b, v129
	v_exp_f32_e32 v160, v157
	v_rcp_f32_e32 v157, v158
	v_add_f32_e32 v158, 1.0, v159
	v_rcp_f32_e32 v158, v158
	v_add_f32_e32 v159, 1.0, v160
	v_rcp_f32_e32 v159, v159
	v_pk_mul_f32 v[126:127], v[126:127], v[156:157]
	v_pk_mul_f32 v[122:123], v[122:123], v[144:145] op_sel_hi:[1,0]
	v_pk_mul_f32 v[118:119], v[118:119], v[126:127]
	v_pk_mul_f32 v[126:127], v[128:129], v[158:159]
	v_mul_f32_e32 v128, 0xbfb8aa3b, v122
	v_exp_f32_e32 v128, v128
	v_pk_mul_f32 v[120:121], v[120:121], v[144:145] op_sel_hi:[1,0]
	v_pk_mul_f32 v[124:125], v[124:125], v[144:145] op_sel_hi:[1,0]
	v_pk_mul_f32 v[120:121], v[120:121], v[126:127]
	v_mul_f32_e32 v126, 0xbfb8aa3b, v123
	v_exp_f32_e32 v127, v126
	v_add_f32_e32 v126, 1.0, v128
	v_mul_f32_e32 v128, 0xbfb8aa3b, v124
	v_mul_f32_e32 v129, 0xbfb8aa3b, v125
	v_exp_f32_e32 v128, v128
	v_exp_f32_e32 v129, v129
	v_add_f32_e32 v127, 1.0, v127
	v_rcp_f32_e32 v126, v126
	v_rcp_f32_e32 v127, v127
	v_add_f32_e32 v128, 1.0, v128
	v_add_f32_e32 v129, 1.0, v129
	v_rcp_f32_e32 v128, v128
	v_rcp_f32_e32 v129, v129
	v_pk_mul_f32 v[114:115], v[114:115], v[144:145] op_sel_hi:[1,0]
	v_pk_mul_f32 v[122:123], v[122:123], v[126:127]
	v_ashrrev_i32_e32 v155, 31, v154
	v_pk_mul_f32 v[122:123], v[114:115], v[122:123]
	v_pk_mul_f32 v[114:115], v[116:117], v[144:145] op_sel_hi:[1,0]
	v_pk_mul_f32 v[116:117], v[124:125], v[128:129]
	v_or_b32_e32 v127, 32, v152
	v_pk_mul_f32 v[124:125], v[114:115], v[116:117]
	v_cvt_pk_bf16_f32 v114, v118, v119
	v_mov_b64_e32 v[118:119], s[6:7]
	v_cvt_pk_bf16_f32 v115, v120, v121
	v_cvt_pk_bf16_f32 v116, v122, v123
	v_mad_i64_i32 v[122:123], s[26:27], v152, s50, v[118:119]
	v_lshlrev_b64 v[120:121], 1, v[154:155]
	v_cvt_pk_bf16_f32 v117, v124, v125
	v_lshl_add_u64 v[124:125], v[122:123], 0, v[120:121]
	v_or_b32_e32 v123, 16, v152
	v_lshl_add_u32 v122, v123, 2, s2
	ds_read_b32 v122, v122
	v_or_b32_e32 v129, 48, v152
	v_lshl_add_u32 v126, v127, 2, s2
	v_lshl_add_u32 v128, v129, 2, s2
	ds_read_b32 v144, v126
	ds_read_b32 v126, v128
	ds_read_b32 v128, v153 offset:704
	s_waitcnt lgkmcnt(0)
	v_pk_mul_f32 v[110:111], v[110:111], v[122:123] op_sel_hi:[1,0]
	global_store_dwordx4 v[124:125], v[114:117], off nt
	v_mul_f32_e32 v154, 0xbfb8aa3b, v110
	v_pk_mul_f32 v[112:113], v[112:113], v[122:123] op_sel_hi:[1,0]
	v_mul_f32_e32 v114, 0xbfb8aa3b, v111
	v_exp_f32_e32 v154, v154
	v_exp_f32_e32 v115, v114
	v_mul_f32_e32 v116, 0xbfb8aa3b, v112
	v_mul_f32_e32 v117, 0xbfb8aa3b, v113
	v_exp_f32_e32 v116, v116
	v_exp_f32_e32 v117, v117
	v_add_f32_e32 v114, 1.0, v154
	v_add_f32_e32 v115, 1.0, v115
	v_rcp_f32_e32 v114, v114
	v_rcp_f32_e32 v115, v115
	v_add_f32_e32 v116, 1.0, v116
	v_add_f32_e32 v117, 1.0, v117
	v_rcp_f32_e32 v116, v116
	v_rcp_f32_e32 v117, v117
	v_pk_mul_f32 v[102:103], v[102:103], v[122:123] op_sel_hi:[1,0]
	v_pk_mul_f32 v[110:111], v[110:111], v[114:115]
	v_pk_mul_f32 v[106:107], v[106:107], v[122:123] op_sel_hi:[1,0]
	v_pk_mul_f32 v[102:103], v[102:103], v[110:111]
	v_pk_mul_f32 v[110:111], v[112:113], v[116:117]
	v_mul_f32_e32 v112, 0xbfb8aa3b, v106
	v_exp_f32_e32 v112, v112
	v_pk_mul_f32 v[104:105], v[104:105], v[122:123] op_sel_hi:[1,0]
	v_pk_mul_f32 v[108:109], v[108:109], v[122:123] op_sel_hi:[1,0]
	v_pk_mul_f32 v[104:105], v[104:105], v[110:111]
	v_mul_f32_e32 v110, 0xbfb8aa3b, v107
	v_exp_f32_e32 v111, v110
	v_add_f32_e32 v110, 1.0, v112
	v_mul_f32_e32 v112, 0xbfb8aa3b, v108
	v_mul_f32_e32 v113, 0xbfb8aa3b, v109
	v_exp_f32_e32 v112, v112
	v_exp_f32_e32 v113, v113
	v_add_f32_e32 v111, 1.0, v111
	v_rcp_f32_e32 v110, v110
	v_rcp_f32_e32 v111, v111
	v_add_f32_e32 v112, 1.0, v112
	v_add_f32_e32 v113, 1.0, v113
	v_rcp_f32_e32 v112, v112
	v_rcp_f32_e32 v113, v113
	v_pk_mul_f32 v[94:95], v[94:95], v[122:123] op_sel_hi:[1,0]
	v_pk_mul_f32 v[106:107], v[106:107], v[110:111]
	v_pk_mul_f32 v[98:99], v[98:99], v[144:145] op_sel_hi:[1,0]
	v_pk_mul_f32 v[106:107], v[94:95], v[106:107]
	v_pk_mul_f32 v[94:95], v[96:97], v[122:123] op_sel_hi:[1,0]
	v_pk_mul_f32 v[96:97], v[108:109], v[112:113]
	v_pk_mul_f32 v[86:87], v[86:87], v[144:145] op_sel_hi:[1,0]
	v_pk_mul_f32 v[108:109], v[94:95], v[96:97]
	v_cvt_pk_bf16_f32 v94, v102, v103
	v_mad_i64_i32 v[102:103], s[26:27], v123, s50, v[118:119]
	v_cvt_pk_bf16_f32 v95, v104, v105
	v_cvt_pk_bf16_f32 v96, v106, v107
	v_cvt_pk_bf16_f32 v97, v108, v109
	v_lshl_add_u64 v[102:103], v[102:103], 0, v[120:121]
	v_mul_f32_e32 v104, 0xbfb8aa3b, v98
	global_store_dwordx4 v[102:103], v[94:97], off nt
	v_exp_f32_e32 v104, v104
	v_pk_mul_f32 v[90:91], v[90:91], v[144:145] op_sel_hi:[1,0]
	v_mul_f32_e32 v94, 0xbfb8aa3b, v99
	v_pk_mul_f32 v[96:97], v[100:101], v[144:145] op_sel_hi:[1,0]
	v_exp_f32_e32 v95, v94
	v_mul_f32_e32 v100, 0xbfb8aa3b, v96
	v_mul_f32_e32 v101, 0xbfb8aa3b, v97
	v_exp_f32_e32 v100, v100
	v_exp_f32_e32 v101, v101
	v_add_f32_e32 v94, 1.0, v104
	v_add_f32_e32 v95, 1.0, v95
	v_rcp_f32_e32 v94, v94
	v_rcp_f32_e32 v95, v95
	v_add_f32_e32 v100, 1.0, v100
	v_add_f32_e32 v101, 1.0, v101
	v_rcp_f32_e32 v100, v100
	v_rcp_f32_e32 v101, v101
	v_pk_mul_f32 v[94:95], v[98:99], v[94:95]
	v_pk_mul_f32 v[88:89], v[88:89], v[144:145] op_sel_hi:[1,0]
	v_pk_mul_f32 v[86:87], v[86:87], v[94:95]
	v_pk_mul_f32 v[94:95], v[96:97], v[100:101]
	v_mul_f32_e32 v96, 0xbfb8aa3b, v90
	v_exp_f32_e32 v96, v96
	v_pk_mul_f32 v[88:89], v[88:89], v[94:95]
	v_mul_f32_e32 v94, 0xbfb8aa3b, v91
	v_pk_mul_f32 v[92:93], v[92:93], v[144:145] op_sel_hi:[1,0]
	v_exp_f32_e32 v95, v94
	v_add_f32_e32 v94, 1.0, v96
	v_mul_f32_e32 v96, 0xbfb8aa3b, v92
	v_mul_f32_e32 v97, 0xbfb8aa3b, v93
	v_exp_f32_e32 v96, v96
	v_exp_f32_e32 v97, v97
	v_add_f32_e32 v95, 1.0, v95
	v_rcp_f32_e32 v94, v94
	v_rcp_f32_e32 v95, v95
	v_add_f32_e32 v96, 1.0, v96
	v_add_f32_e32 v97, 1.0, v97
	v_rcp_f32_e32 v96, v96
	v_rcp_f32_e32 v97, v97
	v_pk_mul_f32 v[78:79], v[78:79], v[144:145] op_sel_hi:[1,0]
	v_pk_mul_f32 v[90:91], v[90:91], v[94:95]
	v_pk_mul_f32 v[82:83], v[82:83], v[126:127] op_sel_hi:[1,0]
	v_pk_mul_f32 v[90:91], v[78:79], v[90:91]
	v_pk_mul_f32 v[78:79], v[80:81], v[144:145] op_sel_hi:[1,0]
	v_pk_mul_f32 v[80:81], v[92:93], v[96:97]
	v_pk_mul_f32 v[70:71], v[70:71], v[126:127] op_sel_hi:[1,0]
	v_pk_mul_f32 v[92:93], v[78:79], v[80:81]
	v_cvt_pk_bf16_f32 v78, v86, v87
	v_mad_i64_i32 v[86:87], s[26:27], v127, s50, v[118:119]
	v_cvt_pk_bf16_f32 v79, v88, v89
	v_cvt_pk_bf16_f32 v80, v90, v91
	v_cvt_pk_bf16_f32 v81, v92, v93
	v_lshl_add_u64 v[86:87], v[86:87], 0, v[120:121]
	v_mul_f32_e32 v88, 0xbfb8aa3b, v82
	global_store_dwordx4 v[86:87], v[78:81], off nt
	v_exp_f32_e32 v88, v88
	v_pk_mul_f32 v[74:75], v[74:75], v[126:127] op_sel_hi:[1,0]
	v_mul_f32_e32 v78, 0xbfb8aa3b, v83
	v_pk_mul_f32 v[80:81], v[84:85], v[126:127] op_sel_hi:[1,0]
	v_exp_f32_e32 v79, v78
	v_mul_f32_e32 v84, 0xbfb8aa3b, v80
	v_mul_f32_e32 v85, 0xbfb8aa3b, v81
	v_exp_f32_e32 v84, v84
	v_exp_f32_e32 v85, v85
	v_add_f32_e32 v78, 1.0, v88
	v_add_f32_e32 v79, 1.0, v79
	v_rcp_f32_e32 v78, v78
	v_rcp_f32_e32 v79, v79
	v_add_f32_e32 v84, 1.0, v84
	v_add_f32_e32 v85, 1.0, v85
	v_rcp_f32_e32 v84, v84
	v_rcp_f32_e32 v85, v85
	v_pk_mul_f32 v[78:79], v[82:83], v[78:79]
	v_pk_mul_f32 v[72:73], v[72:73], v[126:127] op_sel_hi:[1,0]
	v_pk_mul_f32 v[70:71], v[70:71], v[78:79]
	v_pk_mul_f32 v[78:79], v[80:81], v[84:85]
	v_mul_f32_e32 v80, 0xbfb8aa3b, v74
	v_exp_f32_e32 v80, v80
	v_pk_mul_f32 v[72:73], v[72:73], v[78:79]
	v_mul_f32_e32 v78, 0xbfb8aa3b, v75
	v_pk_mul_f32 v[76:77], v[76:77], v[126:127] op_sel_hi:[1,0]
	v_exp_f32_e32 v79, v78
	v_add_f32_e32 v78, 1.0, v80
	v_mul_f32_e32 v80, 0xbfb8aa3b, v76
	v_mul_f32_e32 v81, 0xbfb8aa3b, v77
	v_exp_f32_e32 v80, v80
	v_exp_f32_e32 v81, v81
	v_add_f32_e32 v79, 1.0, v79
	v_rcp_f32_e32 v78, v78
	v_rcp_f32_e32 v79, v79
	v_add_f32_e32 v80, 1.0, v80
	v_add_f32_e32 v81, 1.0, v81
	v_rcp_f32_e32 v80, v80
	v_rcp_f32_e32 v81, v81
	v_pk_mul_f32 v[66:67], v[66:67], v[126:127] op_sel_hi:[1,0]
	v_pk_mul_f32 v[74:75], v[74:75], v[78:79]
	v_pk_mul_f32 v[14:15], v[14:15], v[128:129] op_sel_hi:[1,0]
	v_pk_mul_f32 v[74:75], v[66:67], v[74:75]
	v_pk_mul_f32 v[66:67], v[68:69], v[126:127] op_sel_hi:[1,0]
	v_pk_mul_f32 v[68:69], v[76:77], v[80:81]
	v_pk_mul_f32 v[16:17], v[16:17], v[128:129] op_sel_hi:[1,0]
	v_pk_mul_f32 v[76:77], v[66:67], v[68:69]
	v_cvt_pk_bf16_f32 v66, v70, v71
	v_mad_i64_i32 v[70:71], s[26:27], v129, s50, v[118:119]
	v_cvt_pk_bf16_f32 v67, v72, v73
	v_cvt_pk_bf16_f32 v68, v74, v75
	v_cvt_pk_bf16_f32 v69, v76, v77
	v_lshl_add_u64 v[70:71], v[70:71], 0, v[120:121]
	global_store_dwordx4 v[70:71], v[66:69], off nt
	v_add_u32_e32 v72, 0x80, v152
	v_pk_mul_f32 v[6:7], v[6:7], v[128:129] op_sel_hi:[1,0]
	v_mov_b32_e32 v66, v145
	v_pk_mul_f32 v[62:63], v[62:63], v[66:67] op_sel_hi:[1,0]
	v_pk_mul_f32 v[10:11], v[10:11], v[128:129] op_sel_hi:[1,0]
	v_mul_f32_e32 v67, 0xbfb8aa3b, v62
	v_exp_f32_e32 v67, v67
	v_mul_f32_e32 v68, 0xbfb8aa3b, v63
	v_exp_f32_e32 v69, v68
	v_pk_mul_f32 v[8:9], v[8:9], v[128:129] op_sel_hi:[1,0]
	v_add_f32_e32 v67, 1.0, v67
	v_rcp_f32_e32 v68, v67
	v_pk_mul_f32 v[54:55], v[54:55], v[66:67] op_sel_hi:[1,0]
	v_add_f32_e32 v67, 1.0, v69
	v_pk_mul_f32 v[64:65], v[64:65], v[66:67] op_sel_hi:[1,0]
	v_pk_mul_f32 v[12:13], v[12:13], v[128:129] op_sel_hi:[1,0]
	v_mul_f32_e32 v69, 0xbfb8aa3b, v64
	v_exp_f32_e32 v70, v69
	v_mul_f32_e32 v69, 0xbfb8aa3b, v65
	v_exp_f32_e32 v71, v69
	v_rcp_f32_e32 v69, v67
	v_add_f32_e32 v67, 1.0, v70
	v_rcp_f32_e32 v70, v67
	v_add_f32_e32 v67, 1.0, v71
	v_rcp_f32_e32 v71, v67
	v_pk_mul_f32 v[62:63], v[62:63], v[68:69]
	v_pk_mul_f32 v[58:59], v[58:59], v[66:67] op_sel_hi:[1,0]
	v_pk_mul_f32 v[54:55], v[54:55], v[62:63]
	v_pk_mul_f32 v[62:63], v[64:65], v[70:71]
	v_mul_f32_e32 v64, 0xbfb8aa3b, v58
	v_exp_f32_e32 v64, v64
	v_pk_mul_f32 v[56:57], v[56:57], v[66:67] op_sel_hi:[1,0]
	v_pk_mul_f32 v[60:61], v[60:61], v[66:67] op_sel_hi:[1,0]
	v_pk_mul_f32 v[56:57], v[56:57], v[62:63]
	v_mul_f32_e32 v62, 0xbfb8aa3b, v59
	v_exp_f32_e32 v63, v62
	v_add_f32_e32 v62, 1.0, v64
	v_mul_f32_e32 v64, 0xbfb8aa3b, v60
	v_mul_f32_e32 v65, 0xbfb8aa3b, v61
	v_exp_f32_e32 v64, v64
	v_exp_f32_e32 v65, v65
	v_add_f32_e32 v63, 1.0, v63
	v_rcp_f32_e32 v62, v62
	v_rcp_f32_e32 v63, v63
	v_add_f32_e32 v64, 1.0, v64
	v_add_f32_e32 v65, 1.0, v65
	v_rcp_f32_e32 v64, v64
	v_rcp_f32_e32 v65, v65
	v_pk_mul_f32 v[46:47], v[46:47], v[66:67] op_sel_hi:[1,0]
	v_pk_mul_f32 v[58:59], v[58:59], v[62:63]
	v_pk_mul_f32 v[2:3], v[2:3], v[128:129] op_sel_hi:[1,0]
	v_pk_mul_f32 v[58:59], v[46:47], v[58:59]
	v_pk_mul_f32 v[46:47], v[48:49], v[66:67] op_sel_hi:[1,0]
	v_pk_mul_f32 v[48:49], v[60:61], v[64:65]
	s_nop 0
	v_pk_mul_f32 v[60:61], v[46:47], v[48:49]
	v_cvt_pk_bf16_f32 v46, v54, v55
	ds_read2_b32 v[54:55], v153 offset0:144 offset1:160
	v_cvt_pk_bf16_f32 v47, v56, v57
	v_mad_i64_i32 v[56:57], s[26:27], v72, s50, v[118:119]
	v_cvt_pk_bf16_f32 v48, v58, v59
	v_cvt_pk_bf16_f32 v49, v60, v61
	v_lshl_add_u64 v[56:57], v[56:57], 0, v[120:121]
	global_store_dwordx4 v[56:57], v[46:49], off nt
	s_waitcnt lgkmcnt(0)
	v_pk_mul_f32 v[42:43], v[42:43], v[54:55] op_sel_hi:[1,0]
	v_pk_mul_f32 v[38:39], v[38:39], v[54:55] op_sel_hi:[1,0]
	v_pk_mul_f32 v[46:47], v[50:51], v[54:55] op_sel_hi:[1,0]
	v_pk_mul_f32 v[50:51], v[52:53], v[54:55] op_sel_hi:[1,0]
	v_mul_f32_e32 v48, 0xbfb8aa3b, v46
	v_mul_f32_e32 v49, 0xbfb8aa3b, v47
	v_exp_f32_e32 v48, v48
	v_exp_f32_e32 v49, v49
	v_mul_f32_e32 v52, 0xbfb8aa3b, v50
	v_mul_f32_e32 v53, 0xbfb8aa3b, v51
	v_exp_f32_e32 v52, v52
	v_exp_f32_e32 v53, v53
	v_add_f32_e32 v48, 1.0, v48
	v_add_f32_e32 v49, 1.0, v49
	v_rcp_f32_e32 v48, v48
	v_rcp_f32_e32 v49, v49
	v_add_f32_e32 v52, 1.0, v52
	v_add_f32_e32 v53, 1.0, v53
	v_rcp_f32_e32 v52, v52
	v_rcp_f32_e32 v53, v53
	v_pk_mul_f32 v[46:47], v[46:47], v[48:49]
	v_mul_f32_e32 v48, 0xbfb8aa3b, v42
	v_exp_f32_e32 v48, v48
	v_pk_mul_f32 v[38:39], v[38:39], v[46:47]
	v_pk_mul_f32 v[40:41], v[40:41], v[54:55] op_sel_hi:[1,0]
	v_pk_mul_f32 v[46:47], v[50:51], v[52:53]
	v_pk_mul_f32 v[44:45], v[44:45], v[54:55] op_sel_hi:[1,0]
	v_pk_mul_f32 v[40:41], v[40:41], v[46:47]
	v_mul_f32_e32 v46, 0xbfb8aa3b, v43
	v_exp_f32_e32 v47, v46
	v_add_f32_e32 v46, 1.0, v48
	v_mul_f32_e32 v48, 0xbfb8aa3b, v44
	v_mul_f32_e32 v49, 0xbfb8aa3b, v45
	v_exp_f32_e32 v48, v48
	v_exp_f32_e32 v49, v49
	v_add_f32_e32 v47, 1.0, v47
	v_rcp_f32_e32 v46, v46
	v_rcp_f32_e32 v47, v47
	v_add_f32_e32 v48, 1.0, v48
	v_add_f32_e32 v49, 1.0, v49
	v_rcp_f32_e32 v48, v48
	v_rcp_f32_e32 v49, v49
	v_pk_mul_f32 v[30:31], v[30:31], v[54:55] op_sel_hi:[1,0]
	v_pk_mul_f32 v[42:43], v[42:43], v[46:47]
	v_add_u32_e32 v56, 0x90, v152
	v_pk_mul_f32 v[42:43], v[30:31], v[42:43]
	v_pk_mul_f32 v[30:31], v[32:33], v[54:55] op_sel_hi:[1,0]
	v_pk_mul_f32 v[32:33], v[44:45], v[48:49]
	s_nop 0
	v_pk_mul_f32 v[44:45], v[30:31], v[32:33]
	v_cvt_pk_bf16_f32 v30, v38, v39
	v_mad_i64_i32 v[38:39], s[26:27], v56, s50, v[118:119]
	v_cvt_pk_bf16_f32 v31, v40, v41
	v_cvt_pk_bf16_f32 v32, v42, v43
	v_cvt_pk_bf16_f32 v33, v44, v45
	v_lshl_add_u64 v[38:39], v[38:39], 0, v[120:121]
	global_store_dwordx4 v[38:39], v[30:33], off nt
	v_add_u32_e32 v40, 0xa0, v152
	s_nop 0
	v_mov_b32_e32 v30, v55
	v_pk_mul_f32 v[32:33], v[34:35], v[30:31] op_sel_hi:[1,0]
	s_nop 0
	v_mul_f32_e32 v31, 0xbfb8aa3b, v32
	v_exp_f32_e32 v31, v31
	v_mul_f32_e32 v34, 0xbfb8aa3b, v33
	v_exp_f32_e32 v35, v34
	v_add_f32_e32 v31, 1.0, v31
	v_rcp_f32_e32 v34, v31
	v_pk_mul_f32 v[22:23], v[22:23], v[30:31] op_sel_hi:[1,0]
	v_add_f32_e32 v31, 1.0, v35
	v_pk_mul_f32 v[36:37], v[36:37], v[30:31] op_sel_hi:[1,0]
	s_nop 0
	v_mul_f32_e32 v35, 0xbfb8aa3b, v36
	v_exp_f32_e32 v38, v35
	v_mul_f32_e32 v35, 0xbfb8aa3b, v37
	v_exp_f32_e32 v39, v35
	v_rcp_f32_e32 v35, v31
	v_add_f32_e32 v31, 1.0, v38
	v_rcp_f32_e32 v38, v31
	v_add_f32_e32 v31, 1.0, v39
	v_rcp_f32_e32 v39, v31
	v_pk_mul_f32 v[32:33], v[32:33], v[34:35]
	v_pk_mul_f32 v[26:27], v[26:27], v[30:31] op_sel_hi:[1,0]
	v_pk_mul_f32 v[22:23], v[22:23], v[32:33]
	v_pk_mul_f32 v[24:25], v[24:25], v[30:31] op_sel_hi:[1,0]
	v_pk_mul_f32 v[32:33], v[36:37], v[38:39]
	v_mul_f32_e32 v31, 0xbfb8aa3b, v26
	v_exp_f32_e32 v31, v31
	v_pk_mul_f32 v[24:25], v[24:25], v[32:33]
	v_mul_f32_e32 v32, 0xbfb8aa3b, v27
	v_exp_f32_e32 v33, v32
	v_add_f32_e32 v31, 1.0, v31
	v_rcp_f32_e32 v32, v31
	v_pk_mul_f32 v[18:19], v[18:19], v[30:31] op_sel_hi:[1,0]
	v_add_f32_e32 v31, 1.0, v33
	v_pk_mul_f32 v[28:29], v[28:29], v[30:31] op_sel_hi:[1,0]
	s_nop 0
	v_mul_f32_e32 v33, 0xbfb8aa3b, v28
	v_exp_f32_e32 v34, v33
	v_mul_f32_e32 v33, 0xbfb8aa3b, v29
	v_exp_f32_e32 v35, v33
	v_rcp_f32_e32 v33, v31
	v_add_f32_e32 v31, 1.0, v34
	v_rcp_f32_e32 v34, v31
	v_add_f32_e32 v31, 1.0, v35
	v_rcp_f32_e32 v35, v31
	v_pk_mul_f32 v[26:27], v[26:27], v[32:33]
	s_nop 0
	v_pk_mul_f32 v[26:27], v[18:19], v[26:27]
	v_pk_mul_f32 v[18:19], v[20:21], v[30:31] op_sel_hi:[1,0]
	v_pk_mul_f32 v[20:21], v[28:29], v[34:35]
	s_nop 0
	v_pk_mul_f32 v[28:29], v[18:19], v[20:21]
	v_cvt_pk_bf16_f32 v18, v22, v23
	v_mad_i64_i32 v[22:23], s[26:27], v40, s50, v[118:119]
	v_cvt_pk_bf16_f32 v19, v24, v25
	v_cvt_pk_bf16_f32 v20, v26, v27
	v_cvt_pk_bf16_f32 v21, v28, v29
	v_lshl_add_u64 v[22:23], v[22:23], 0, v[120:121]
	global_store_dwordx4 v[22:23], v[18:21], off nt
	v_add_u32_e32 v22, 0xb0, v152
	s_nop 0
	v_mul_f32_e32 v18, 0xbfb8aa3b, v14
	v_mul_f32_e32 v19, 0xbfb8aa3b, v15
	v_exp_f32_e32 v18, v18
	v_exp_f32_e32 v19, v19
	v_mul_f32_e32 v20, 0xbfb8aa3b, v16
	v_mul_f32_e32 v21, 0xbfb8aa3b, v17
	v_exp_f32_e32 v20, v20
	v_exp_f32_e32 v21, v21
	v_add_f32_e32 v18, 1.0, v18
	v_add_f32_e32 v19, 1.0, v19
	v_rcp_f32_e32 v18, v18
	v_rcp_f32_e32 v19, v19
	v_add_f32_e32 v20, 1.0, v20
	v_add_f32_e32 v21, 1.0, v21
	v_rcp_f32_e32 v20, v20
	v_rcp_f32_e32 v21, v21
	v_pk_mul_f32 v[14:15], v[14:15], v[18:19]
	s_nop 0
	v_pk_mul_f32 v[6:7], v[6:7], v[14:15]
	v_pk_mul_f32 v[14:15], v[16:17], v[20:21]
	v_mul_f32_e32 v16, 0xbfb8aa3b, v10
	v_exp_f32_e32 v16, v16
	v_pk_mul_f32 v[8:9], v[8:9], v[14:15]
	v_mul_f32_e32 v14, 0xbfb8aa3b, v11
	v_exp_f32_e32 v15, v14
	v_add_f32_e32 v14, 1.0, v16
	v_mul_f32_e32 v16, 0xbfb8aa3b, v12
	v_mul_f32_e32 v17, 0xbfb8aa3b, v13
	v_exp_f32_e32 v16, v16
	v_exp_f32_e32 v17, v17
	v_add_f32_e32 v15, 1.0, v15
	v_rcp_f32_e32 v14, v14
	v_rcp_f32_e32 v15, v15
	v_add_f32_e32 v16, 1.0, v16
	v_add_f32_e32 v17, 1.0, v17
	v_rcp_f32_e32 v16, v16
	v_rcp_f32_e32 v17, v17
	v_pk_mul_f32 v[10:11], v[10:11], v[14:15]
	s_nop 0
	v_pk_mul_f32 v[10:11], v[2:3], v[10:11]
	v_pk_mul_f32 v[2:3], v[4:5], v[128:129] op_sel_hi:[1,0]
	v_pk_mul_f32 v[4:5], v[12:13], v[16:17]
	s_nop 0
	v_pk_mul_f32 v[12:13], v[2:3], v[4:5]
	v_cvt_pk_bf16_f32 v2, v6, v7
	v_mad_i64_i32 v[6:7], s[26:27], v22, s50, v[118:119]
	v_cvt_pk_bf16_f32 v3, v8, v9
	v_cvt_pk_bf16_f32 v4, v10, v11
	v_cvt_pk_bf16_f32 v5, v12, v13
	v_lshl_add_u64 v[6:7], v[6:7], 0, v[120:121]
	global_store_dwordx4 v[6:7], v[2:5], off nt
	s_cbranch_vccnz .LBB0_1637
	s_andn2_b64 vcc, exec, s[4:5]
	s_cbranch_vccnz .LBB0_1636
	s_barrier
	s_branch .LBB0_1636
